# v17 + the same LDS-DMA balance (4/4/4/4, waits 8/6/8/6) in the P1, P4 out-proj, P4 PLE-proj and P7 K loops
# speedup vs baseline: 1.0118x; 1.0055x over previous
.LBB0_196:
	s_mov_b64 s[92:93], 0x80
	v_lshl_add_u64 v[8:9], v[8:9], 0, s[92:93]
	s_add_i32 m0, s90, 0x18000
	s_waitcnt vmcnt(2)
	s_barrier
	global_load_lds_dwordx4 v[8:9], off
	v_lshl_add_u64 v[4:5], v[4:5], 0, s[92:93]
	s_add_i32 m0, s90, 0x1a000
	s_add_i32 s33, s90, 0x8000
	global_load_lds_dwordx4 v[4:5], off
	v_mov_b32_e32 v242, v6
	v_mov_b32_e32 v243, v7
	v_mov_b32_e32 v244, v10
	v_mov_b32_e32 v245, v11
	v_lshl_add_u64 v[4:5], v[6:7], 0, s[92:93]
	s_mov_b32 m0, s33
	s_add_i32 s28, s90, 0xa000
	global_load_lds_dwordx4 v[4:5], off
	v_lshl_add_u64 v[4:5], v[10:11], 0, s[92:93]
	s_mov_b32 m0, s28
	v_lshl_add_u64 v[2:3], v[2:3], 0, s[92:93]
	global_load_lds_dwordx4 v[4:5], off
	s_add_i32 m0, s90, 0x1c000
	v_lshl_add_u64 v[0:1], v[0:1], 0, s[92:93]
	global_load_lds_dwordx4 v[2:3], off
	s_add_i32 m0, s90, 0x1e000
	s_lshr_b32 s5, s5, 26
	global_load_lds_dwordx4 v[0:1], off
	s_add_i32 s5, s4, s5
	v_and_b32_e32 v141, 15, v12
	s_ashr_i32 s36, s5, 6
	v_readlane_b32 s5, v248, 17
	v_and_b32_e32 v3, 48, v12
	v_and_b32_e32 v4, 0xfffffc00, v16
	v_or_b32_e32 v1, s5, v141
	v_lshlrev_b32_e32 v2, 6, v1
	s_movk_i32 s5, 0x3c0
	v_and_or_b32 v2, v2, s5, v3
	v_readlane_b32 s5, v248, 25
	v_lshlrev_b32_e32 v1, 2, v1
	v_and_b32_e32 v1, 32, v1
	v_lshl_add_u32 v5, s5, 13, v4
	v_bitop3_b32 v1, v2, v5, v1 bitop3:0xde
	v_lshl_or_b32 v2, v141, 6, v3
	v_lshl_add_u32 v3, s29, 12, v4
	v_lshlrev_b32_e32 v4, 2, v12
	s_lshl_b32 s5, s5, 12
	v_and_b32_e32 v4, 32, v4
	s_lshl_b32 s6, s29, 10
	s_add_i32 s5, s5, 0
	v_ashrrev_i32_e32 v0, 4, v12
	v_bitop3_b32 v143, v2, v3, v4 bitop3:0xde
	s_add_i32 s5, s5, s6
	v_ashrrev_i32_e32 v2, 1, v12
	v_lshlrev_b32_e32 v4, 3, v12
	v_lshlrev_b32_e32 v138, 3, v0
	s_add_i32 s5, s5, 0x20100
	v_lshlrev_b32_e32 v3, 5, v2
	v_and_b32_e32 v140, 8, v4
	v_add_u32_e32 v162, 0xfffffc00, v2
	v_lshlrev_b32_e32 v0, 8, v0
	v_lshlrev_b32_e32 v2, 1, v141
	v_add3_u32 v163, s5, v2, v0
	v_lshlrev_b32_e32 v0, 1, v140
	v_add3_u32 v164, s5, v3, v0
	v_add_u32_e32 v0, v15, v13
	s_waitcnt vmcnt(6)
	s_cmp_gt_i32 s4, 63
	v_add_lshl_u32 v136, v0, v14, 1
	v_add_u32_e32 v0, v19, v17
	s_cselect_b64 s[64:65], -1, 0
	v_subrev_co_u32_e64 v142, s[18:19], 13, v141
	v_lshl_add_u64 v[144:145], s[74:75], 0, v[136:137]
	v_add_lshl_u32 v136, v0, v18, 1
	s_add_i32 s37, 0, 0x10000
	s_add_i32 s38, 0, 0x14000
	s_mov_b32 s53, 0x8000
	s_add_i32 s52, s36, -2
	s_xor_b64 s[84:85], s[18:19], -1
	v_ashrrev_i32_e32 v139, 31, v138
	v_or_b32_e32 v165, 16, v141
	v_or_b32_e32 v166, 32, v141
	v_or_b32_e32 v167, 48, v141
	v_lshl_add_u64 v[146:147], s[74:75], 0, v[136:137]
	v_mov_b64_e32 v[148:149], 0x528
	v_mov_b64_e32 v[150:151], 0x527
	v_add_u32_e32 v168, s37, v143
	v_add_u32_e32 v169, s38, v143
	v_add_u32_e32 v170, 0, v1
	s_movk_i32 s39, 0x1400
	s_mov_b32 s40, 0x10800
	s_movk_i32 s41, 0x7fff
	s_movk_i32 s42, 0x3ffc
	v_mov_b32_e32 v171, 0x3e38aa3b
	s_barrier
	s_branch .LBB0_199

.LBB0_205:
	s_andn2_b64 vcc, exec, s[64:65]
	s_cbranch_vccnz .Lzx207
	s_add_u32 s6, s10, 0x80
	s_addc_u32 s7, s11, 0
	s_add_u32 s10, s8, 0x100
	s_addc_u32 s11, s9, 0
	s_mov_b32 s8, 0
	ds_read_b128 v[152:155], v168
	ds_read_b128 v[156:159], v168 offset:1024
	ds_read_b128 v[172:175], v168 offset:2048
	ds_read_b128 v[176:179], v168 offset:3072
	ds_read_b128 v[180:183], v169
	ds_read_b128 v[186:189], v169 offset:1024
	ds_read_b128 v[190:193], v169 offset:2048
	ds_read_b128 v[194:197], v169 offset:3072
	s_add_i32 s12, s8, 2
	s_add_u32 s13, s6, 0x80
	s_addc_u32 s9, s7, 0
	s_cmp_eq_u32 s52, s8
	s_cselect_b32 s8, s86, s13
	s_cselect_b32 s9, s87, s9
	s_cselect_b32 s17, s89, s11
	s_cselect_b32 s16, s88, s10
	v_lshl_add_u64 v[160:161], v[242:243], 0, s[92:93]
	s_mov_b32 m0, s33
	s_nop 0
	global_load_lds_dwordx4 v[160:161], off
	v_lshl_add_u64 v[160:161], v[244:245], 0, s[92:93]
	s_mov_b32 m0, s28
	s_nop 0
	global_load_lds_dwordx4 v[160:161], off
	v_lshl_add_u64 v[160:161], s[6:7], 0, v[144:145]
	s_add_i32 m0, s90, 0xc000
	ds_read_b128 v[198:201], v170
	ds_read_b128 v[202:205], v170 offset:1024
	ds_read_b128 v[206:209], v170 offset:2048
	ds_read_b128 v[210:213], v170 offset:3072
	ds_read_b128 v[214:217], v170 offset:4096
	ds_read_b128 v[224:227], v170 offset:5120
	ds_read_b128 v[228:231], v170 offset:6144
	ds_read_b128 v[232:235], v170 offset:7168
	global_load_lds_dwordx4 v[160:161], off
	v_lshl_add_u64 v[160:161], s[6:7], 0, v[146:147]
	s_add_i32 m0, s90, 0xe000
	s_nop 0
	global_load_lds_dwordx4 v[160:161], off
	s_waitcnt vmcnt(8)
	s_waitcnt lgkmcnt(0)
	s_barrier
	s_setprio 1
	s_waitcnt lgkmcnt(0)
	v_mfma_f32_16x16x32_bf16 v[124:127], v[152:155], v[198:201], 0
	v_mfma_f32_16x16x32_bf16 v[120:123], v[172:175], v[198:201], 0
	v_mfma_f32_16x16x32_bf16 v[108:111], v[152:155], v[206:209], 0
	v_mfma_f32_16x16x32_bf16 v[104:107], v[172:175], v[206:209], 0
	v_mfma_f32_16x16x32_bf16 v[92:95], v[152:155], v[214:217], 0
	v_mfma_f32_16x16x32_bf16 v[88:91], v[172:175], v[214:217], 0
	v_mfma_f32_16x16x32_bf16 v[76:79], v[152:155], v[228:231], 0
	v_mfma_f32_16x16x32_bf16 v[72:75], v[172:175], v[228:231], 0
	v_mfma_f32_16x16x32_bf16 v[124:127], v[156:159], v[202:205], v[124:127]
	v_mfma_f32_16x16x32_bf16 v[120:123], v[176:179], v[202:205], v[120:123]
	v_mfma_f32_16x16x32_bf16 v[108:111], v[156:159], v[210:213], v[108:111]
	v_mfma_f32_16x16x32_bf16 v[104:107], v[176:179], v[210:213], v[104:107]
	v_mfma_f32_16x16x32_bf16 v[92:95], v[156:159], v[224:227], v[92:95]
	v_mfma_f32_16x16x32_bf16 v[88:91], v[176:179], v[224:227], v[88:91]
	v_mfma_f32_16x16x32_bf16 v[76:79], v[156:159], v[232:235], v[76:79]
	v_mfma_f32_16x16x32_bf16 v[72:75], v[176:179], v[232:235], v[72:75]
	s_setprio 0
	s_setprio 1
	v_mfma_f32_16x16x32_bf16 v[116:119], v[180:183], v[198:201], 0
	v_mfma_f32_16x16x32_bf16 v[112:115], v[190:193], v[198:201], 0
	v_mfma_f32_16x16x32_bf16 v[100:103], v[180:183], v[206:209], 0
	v_mfma_f32_16x16x32_bf16 v[96:99], v[190:193], v[206:209], 0
	v_mfma_f32_16x16x32_bf16 v[84:87], v[180:183], v[214:217], 0
	v_mfma_f32_16x16x32_bf16 v[80:83], v[190:193], v[214:217], 0
	v_mfma_f32_16x16x32_bf16 v[68:71], v[180:183], v[228:231], 0
	v_mfma_f32_16x16x32_bf16 v[64:67], v[190:193], v[228:231], 0
	v_mfma_f32_16x16x32_bf16 v[116:119], v[186:189], v[202:205], v[116:119]
	v_mfma_f32_16x16x32_bf16 v[112:115], v[194:197], v[202:205], v[112:115]
	v_mfma_f32_16x16x32_bf16 v[100:103], v[186:189], v[210:213], v[100:103]
	v_mfma_f32_16x16x32_bf16 v[96:99], v[194:197], v[210:213], v[96:99]
	v_mfma_f32_16x16x32_bf16 v[84:87], v[186:189], v[224:227], v[84:87]
	v_mfma_f32_16x16x32_bf16 v[80:83], v[194:197], v[224:227], v[80:83]
	v_mfma_f32_16x16x32_bf16 v[68:71], v[186:189], v[232:235], v[68:71]
	v_mfma_f32_16x16x32_bf16 v[64:67], v[194:197], v[232:235], v[64:67]
	s_setprio 0
	s_barrier
	s_add_i32 s13, s37, s31
	v_lshl_add_u64 v[160:161], s[16:17], 0, v[130:131]
	s_mov_b32 m0, s13
	ds_read_b128 v[198:201], v170 offset:16384
	ds_read_b128 v[202:205], v170 offset:17408
	ds_read_b128 v[206:209], v170 offset:18432
	ds_read_b128 v[210:213], v170 offset:19456
	ds_read_b128 v[214:217], v170 offset:20480
	ds_read_b128 v[224:227], v170 offset:21504
	ds_read_b128 v[228:231], v170 offset:22528
	ds_read_b128 v[232:235], v170 offset:23552
	global_load_lds_dwordx4 v[160:161], off
	s_add_i32 m0, s13, 0x2000
	v_lshl_add_u64 v[236:237], s[16:17], 0, v[134:135]
	s_add_u32 s16, s16, s74
	s_addc_u32 s17, s17, s75
	s_add_i32 s13, s38, s31
	global_load_lds_dwordx4 v[236:237], off
	v_lshl_add_u64 v[238:239], s[16:17], 0, v[130:131]
	s_mov_b32 m0, s13
	v_lshl_add_u64 v[240:241], s[16:17], 0, v[134:135]
	global_load_lds_dwordx4 v[238:239], off
	s_add_i32 m0, s13, 0x2000
	v_lshl_add_u64 v[242:243], s[8:9], 0, v[128:129]
	global_load_lds_dwordx4 v[240:241], off
	v_lshl_add_u64 v[244:245], s[8:9], 0, v[132:133]
	s_waitcnt vmcnt(6)
	s_waitcnt lgkmcnt(0)
	s_barrier
	s_setprio 1
	s_waitcnt lgkmcnt(0)
	v_mfma_f32_16x16x32_bf16 v[60:63], v[152:155], v[198:201], 0
	v_mfma_f32_16x16x32_bf16 v[56:59], v[172:175], v[198:201], 0
	v_mfma_f32_16x16x32_bf16 v[44:47], v[152:155], v[206:209], 0
	v_mfma_f32_16x16x32_bf16 v[40:43], v[172:175], v[206:209], 0
	v_mfma_f32_16x16x32_bf16 v[28:31], v[152:155], v[214:217], 0
	v_mfma_f32_16x16x32_bf16 v[24:27], v[172:175], v[214:217], 0
	v_mfma_f32_16x16x32_bf16 v[12:15], v[152:155], v[228:231], 0
	v_mfma_f32_16x16x32_bf16 v[8:11], v[172:175], v[228:231], 0
	v_mfma_f32_16x16x32_bf16 v[60:63], v[156:159], v[202:205], v[60:63]
	v_mfma_f32_16x16x32_bf16 v[56:59], v[176:179], v[202:205], v[56:59]
	v_mfma_f32_16x16x32_bf16 v[44:47], v[156:159], v[210:213], v[44:47]
	v_mfma_f32_16x16x32_bf16 v[40:43], v[176:179], v[210:213], v[40:43]
	v_mfma_f32_16x16x32_bf16 v[28:31], v[156:159], v[224:227], v[28:31]
	v_mfma_f32_16x16x32_bf16 v[24:27], v[176:179], v[224:227], v[24:27]
	v_mfma_f32_16x16x32_bf16 v[12:15], v[156:159], v[232:235], v[12:15]
	v_mfma_f32_16x16x32_bf16 v[8:11], v[176:179], v[232:235], v[8:11]
	s_setprio 0
	s_setprio 1
	v_mfma_f32_16x16x32_bf16 v[52:55], v[180:183], v[198:201], 0
	v_mfma_f32_16x16x32_bf16 v[48:51], v[190:193], v[198:201], 0
	v_mfma_f32_16x16x32_bf16 v[36:39], v[180:183], v[206:209], 0
	v_mfma_f32_16x16x32_bf16 v[32:35], v[190:193], v[206:209], 0
	v_mfma_f32_16x16x32_bf16 v[20:23], v[180:183], v[214:217], 0
	v_mfma_f32_16x16x32_bf16 v[16:19], v[190:193], v[214:217], 0
	v_mfma_f32_16x16x32_bf16 v[4:7], v[180:183], v[228:231], 0
	v_mfma_f32_16x16x32_bf16 v[0:3], v[190:193], v[228:231], 0
	v_mfma_f32_16x16x32_bf16 v[52:55], v[186:189], v[202:205], v[52:55]
	v_mfma_f32_16x16x32_bf16 v[48:51], v[194:197], v[202:205], v[48:51]
	v_mfma_f32_16x16x32_bf16 v[36:39], v[186:189], v[210:213], v[36:39]
	v_mfma_f32_16x16x32_bf16 v[32:35], v[194:197], v[210:213], v[32:35]
	v_mfma_f32_16x16x32_bf16 v[20:23], v[186:189], v[224:227], v[20:23]
	v_mfma_f32_16x16x32_bf16 v[16:19], v[194:197], v[224:227], v[16:19]
	v_mfma_f32_16x16x32_bf16 v[4:7], v[186:189], v[232:235], v[4:7]
	v_mfma_f32_16x16x32_bf16 v[0:3], v[194:197], v[232:235], v[0:3]
	s_setprio 0
	s_barrier
	s_add_i32 s13, 0, 0x18000
	v_add_u32_e32 v136, s13, v143
	s_add_i32 s16, 0, 0x1c000
	ds_read_b128 v[152:155], v136
	ds_read_b128 v[156:159], v136 offset:1024
	ds_read_b128 v[172:175], v136 offset:2048
	ds_read_b128 v[176:179], v136 offset:3072
	v_add_u32_e32 v136, s16, v143
	ds_read_b128 v[180:183], v136
	ds_read_b128 v[186:189], v136 offset:1024
	ds_read_b128 v[190:193], v136 offset:2048
	ds_read_b128 v[194:197], v136 offset:3072
	s_add_u32 s8, s8, s74
	s_addc_u32 s9, s9, s75
	s_mov_b32 m0, s90
	s_nop 0
	global_load_lds_dwordx4 v[242:243], off
	s_mov_b32 m0, s91
	s_nop 0
	global_load_lds_dwordx4 v[244:245], off
	s_mov_b32 m0, s78
	v_lshl_add_u64 v[246:247], s[8:9], 0, v[128:129]
	ds_read_b128 v[198:201], v170 offset:32768
	ds_read_b128 v[202:205], v170 offset:33792
	ds_read_b128 v[206:209], v170 offset:34816
	ds_read_b128 v[210:213], v170 offset:35840
	ds_read_b128 v[214:217], v170 offset:36864
	ds_read_b128 v[224:227], v170 offset:37888
	ds_read_b128 v[228:231], v170 offset:38912
	ds_read_b128 v[232:235], v170 offset:39936
	global_load_lds_dwordx4 v[246:247], off
	v_lshl_add_u64 v[246:247], s[8:9], 0, v[132:133]
	s_mov_b32 m0, s79
	s_nop 0
	global_load_lds_dwordx4 v[246:247], off
	s_waitcnt vmcnt(8)
	s_waitcnt lgkmcnt(0)
	s_barrier
	s_setprio 1
	s_waitcnt lgkmcnt(0)
	v_mfma_f32_16x16x32_bf16 v[124:127], v[152:155], v[198:201], v[124:127]
	v_mfma_f32_16x16x32_bf16 v[120:123], v[172:175], v[198:201], v[120:123]
	v_mfma_f32_16x16x32_bf16 v[108:111], v[152:155], v[206:209], v[108:111]
	v_mfma_f32_16x16x32_bf16 v[104:107], v[172:175], v[206:209], v[104:107]
	v_mfma_f32_16x16x32_bf16 v[92:95], v[152:155], v[214:217], v[92:95]
	v_mfma_f32_16x16x32_bf16 v[88:91], v[172:175], v[214:217], v[88:91]
	v_mfma_f32_16x16x32_bf16 v[76:79], v[152:155], v[228:231], v[76:79]
	v_mfma_f32_16x16x32_bf16 v[72:75], v[172:175], v[228:231], v[72:75]
	v_mfma_f32_16x16x32_bf16 v[124:127], v[156:159], v[202:205], v[124:127]
	v_mfma_f32_16x16x32_bf16 v[120:123], v[176:179], v[202:205], v[120:123]
	v_mfma_f32_16x16x32_bf16 v[108:111], v[156:159], v[210:213], v[108:111]
	v_mfma_f32_16x16x32_bf16 v[104:107], v[176:179], v[210:213], v[104:107]
	v_mfma_f32_16x16x32_bf16 v[92:95], v[156:159], v[224:227], v[92:95]
	v_mfma_f32_16x16x32_bf16 v[88:91], v[176:179], v[224:227], v[88:91]
	v_mfma_f32_16x16x32_bf16 v[76:79], v[156:159], v[232:235], v[76:79]
	v_mfma_f32_16x16x32_bf16 v[72:75], v[176:179], v[232:235], v[72:75]
	s_setprio 0
	s_setprio 1
	v_mfma_f32_16x16x32_bf16 v[116:119], v[180:183], v[198:201], v[116:119]
	v_mfma_f32_16x16x32_bf16 v[112:115], v[190:193], v[198:201], v[112:115]
	v_mfma_f32_16x16x32_bf16 v[100:103], v[180:183], v[206:209], v[100:103]
	v_mfma_f32_16x16x32_bf16 v[96:99], v[190:193], v[206:209], v[96:99]
	v_mfma_f32_16x16x32_bf16 v[84:87], v[180:183], v[214:217], v[84:87]
	v_mfma_f32_16x16x32_bf16 v[80:83], v[190:193], v[214:217], v[80:83]
	v_mfma_f32_16x16x32_bf16 v[68:71], v[180:183], v[228:231], v[68:71]
	v_mfma_f32_16x16x32_bf16 v[64:67], v[190:193], v[228:231], v[64:67]
	v_mfma_f32_16x16x32_bf16 v[116:119], v[186:189], v[202:205], v[116:119]
	v_mfma_f32_16x16x32_bf16 v[112:115], v[194:197], v[202:205], v[112:115]
	v_mfma_f32_16x16x32_bf16 v[100:103], v[186:189], v[210:213], v[100:103]
	v_mfma_f32_16x16x32_bf16 v[96:99], v[194:197], v[210:213], v[96:99]
	v_mfma_f32_16x16x32_bf16 v[84:87], v[186:189], v[224:227], v[84:87]
	v_mfma_f32_16x16x32_bf16 v[80:83], v[194:197], v[224:227], v[80:83]
	v_mfma_f32_16x16x32_bf16 v[68:71], v[186:189], v[232:235], v[68:71]
	v_mfma_f32_16x16x32_bf16 v[64:67], v[194:197], v[232:235], v[64:67]
	s_setprio 0
	s_barrier
	s_add_i32 s8, s13, s31
	v_lshl_add_u64 v[160:161], v[160:161], 0, s[92:93]
	s_mov_b32 m0, s8
	ds_read_b128 v[198:201], v170 offset:49152
	ds_read_b128 v[202:205], v170 offset:50176
	ds_read_b128 v[206:209], v170 offset:51200
	ds_read_b128 v[210:213], v170 offset:52224
	ds_read_b128 v[214:217], v170 offset:53248
	ds_read_b128 v[224:227], v170 offset:54272
	ds_read_b128 v[228:231], v170 offset:55296
	ds_read_b128 v[232:235], v170 offset:56320
	global_load_lds_dwordx4 v[160:161], off
	v_lshl_add_u64 v[160:161], v[236:237], 0, s[92:93]
	s_add_i32 m0, s8, 0x2000
	s_add_i32 s8, s16, s31
	global_load_lds_dwordx4 v[160:161], off
	v_lshl_add_u64 v[160:161], v[238:239], 0, s[92:93]
	s_mov_b32 m0, s8
	s_nop 0
	global_load_lds_dwordx4 v[160:161], off
	v_lshl_add_u64 v[160:161], v[240:241], 0, s[92:93]
	s_add_i32 m0, s8, 0x2000
	s_nop 0
	global_load_lds_dwordx4 v[160:161], off
	s_waitcnt vmcnt(6)
	s_waitcnt lgkmcnt(0)
	s_barrier
	s_setprio 1
	s_waitcnt lgkmcnt(0)
	v_mfma_f32_16x16x32_bf16 v[60:63], v[152:155], v[198:201], v[60:63]
	v_mfma_f32_16x16x32_bf16 v[56:59], v[172:175], v[198:201], v[56:59]
	v_mfma_f32_16x16x32_bf16 v[44:47], v[152:155], v[206:209], v[44:47]
	v_mfma_f32_16x16x32_bf16 v[40:43], v[172:175], v[206:209], v[40:43]
	v_mfma_f32_16x16x32_bf16 v[28:31], v[152:155], v[214:217], v[28:31]
	v_mfma_f32_16x16x32_bf16 v[24:27], v[172:175], v[214:217], v[24:27]
	v_mfma_f32_16x16x32_bf16 v[12:15], v[152:155], v[228:231], v[12:15]
	v_mfma_f32_16x16x32_bf16 v[8:11], v[172:175], v[228:231], v[8:11]
	v_mfma_f32_16x16x32_bf16 v[60:63], v[156:159], v[202:205], v[60:63]
	v_mfma_f32_16x16x32_bf16 v[56:59], v[176:179], v[202:205], v[56:59]
	v_mfma_f32_16x16x32_bf16 v[44:47], v[156:159], v[210:213], v[44:47]
	v_mfma_f32_16x16x32_bf16 v[40:43], v[176:179], v[210:213], v[40:43]
	v_mfma_f32_16x16x32_bf16 v[28:31], v[156:159], v[224:227], v[28:31]
	v_mfma_f32_16x16x32_bf16 v[24:27], v[176:179], v[224:227], v[24:27]
	v_mfma_f32_16x16x32_bf16 v[12:15], v[156:159], v[232:235], v[12:15]
	v_mfma_f32_16x16x32_bf16 v[8:11], v[176:179], v[232:235], v[8:11]
	s_setprio 0
	s_setprio 1
	v_mfma_f32_16x16x32_bf16 v[52:55], v[180:183], v[198:201], v[52:55]
	v_mfma_f32_16x16x32_bf16 v[48:51], v[190:193], v[198:201], v[48:51]
	v_mfma_f32_16x16x32_bf16 v[36:39], v[180:183], v[206:209], v[36:39]
	v_mfma_f32_16x16x32_bf16 v[32:35], v[190:193], v[206:209], v[32:35]
	v_mfma_f32_16x16x32_bf16 v[20:23], v[180:183], v[214:217], v[20:23]
	v_mfma_f32_16x16x32_bf16 v[16:19], v[190:193], v[214:217], v[16:19]
	v_mfma_f32_16x16x32_bf16 v[4:7], v[180:183], v[228:231], v[4:7]
	v_mfma_f32_16x16x32_bf16 v[0:3], v[190:193], v[228:231], v[0:3]
	v_mfma_f32_16x16x32_bf16 v[52:55], v[186:189], v[202:205], v[52:55]
	v_mfma_f32_16x16x32_bf16 v[48:51], v[194:197], v[202:205], v[48:51]
	v_mfma_f32_16x16x32_bf16 v[36:39], v[186:189], v[210:213], v[36:39]
	v_mfma_f32_16x16x32_bf16 v[32:35], v[194:197], v[210:213], v[32:35]
	v_mfma_f32_16x16x32_bf16 v[20:23], v[186:189], v[224:227], v[20:23]
	v_mfma_f32_16x16x32_bf16 v[16:19], v[194:197], v[224:227], v[16:19]
	v_mfma_f32_16x16x32_bf16 v[4:7], v[186:189], v[232:235], v[4:7]
	v_mfma_f32_16x16x32_bf16 v[0:3], v[194:197], v[232:235], v[0:3]
	s_setprio 0
	s_barrier
	s_add_u32 s6, s6, 0x100
	s_addc_u32 s7, s7, 0
	s_add_u32 s10, s10, 0x100
	s_addc_u32 s11, s11, 0
	s_cmp_ge_i32 s12, s36
	s_mov_b32 s8, s12
	s_cbranch_scc1 .LBB0_208
.LBB0_207:
	ds_read_b128 v[152:155], v168
	ds_read_b128 v[156:159], v168 offset:1024
	ds_read_b128 v[172:175], v168 offset:2048
	ds_read_b128 v[176:179], v168 offset:3072
	ds_read_b128 v[180:183], v169
	ds_read_b128 v[186:189], v169 offset:1024
	ds_read_b128 v[190:193], v169 offset:2048
	ds_read_b128 v[194:197], v169 offset:3072
	s_add_i32 s12, s8, 2
	s_add_u32 s13, s6, 0x80
	s_addc_u32 s9, s7, 0
	s_cmp_eq_u32 s52, s8
	s_cselect_b32 s8, s86, s13
	s_cselect_b32 s9, s87, s9
	s_cselect_b32 s17, s89, s11
	s_cselect_b32 s16, s88, s10
	v_lshl_add_u64 v[160:161], v[242:243], 0, s[92:93]
	s_mov_b32 m0, s33
	s_nop 0
	global_load_lds_dwordx4 v[160:161], off
	v_lshl_add_u64 v[160:161], v[244:245], 0, s[92:93]
	s_mov_b32 m0, s28
	s_nop 0
	global_load_lds_dwordx4 v[160:161], off
	v_lshl_add_u64 v[160:161], s[6:7], 0, v[144:145]
	s_add_i32 m0, s90, 0xc000
	ds_read_b128 v[198:201], v170
	ds_read_b128 v[202:205], v170 offset:1024
	ds_read_b128 v[206:209], v170 offset:2048
	ds_read_b128 v[210:213], v170 offset:3072
	ds_read_b128 v[214:217], v170 offset:4096
	ds_read_b128 v[224:227], v170 offset:5120
	ds_read_b128 v[228:231], v170 offset:6144
	ds_read_b128 v[232:235], v170 offset:7168
	global_load_lds_dwordx4 v[160:161], off
	v_lshl_add_u64 v[160:161], s[6:7], 0, v[146:147]
	s_add_i32 m0, s90, 0xe000
	s_nop 0
	global_load_lds_dwordx4 v[160:161], off
	s_waitcnt vmcnt(8)
	s_waitcnt lgkmcnt(0)
	s_barrier
	s_setprio 1
	s_waitcnt lgkmcnt(0)
	v_mfma_f32_16x16x32_bf16 v[124:127], v[152:155], v[198:201], v[124:127]
	v_mfma_f32_16x16x32_bf16 v[120:123], v[172:175], v[198:201], v[120:123]
	v_mfma_f32_16x16x32_bf16 v[108:111], v[152:155], v[206:209], v[108:111]
	v_mfma_f32_16x16x32_bf16 v[104:107], v[172:175], v[206:209], v[104:107]
	v_mfma_f32_16x16x32_bf16 v[92:95], v[152:155], v[214:217], v[92:95]
	v_mfma_f32_16x16x32_bf16 v[88:91], v[172:175], v[214:217], v[88:91]
	v_mfma_f32_16x16x32_bf16 v[76:79], v[152:155], v[228:231], v[76:79]
	v_mfma_f32_16x16x32_bf16 v[72:75], v[172:175], v[228:231], v[72:75]
	v_mfma_f32_16x16x32_bf16 v[124:127], v[156:159], v[202:205], v[124:127]
	v_mfma_f32_16x16x32_bf16 v[120:123], v[176:179], v[202:205], v[120:123]
	v_mfma_f32_16x16x32_bf16 v[108:111], v[156:159], v[210:213], v[108:111]
	v_mfma_f32_16x16x32_bf16 v[104:107], v[176:179], v[210:213], v[104:107]
	v_mfma_f32_16x16x32_bf16 v[92:95], v[156:159], v[224:227], v[92:95]
	v_mfma_f32_16x16x32_bf16 v[88:91], v[176:179], v[224:227], v[88:91]
	v_mfma_f32_16x16x32_bf16 v[76:79], v[156:159], v[232:235], v[76:79]
	v_mfma_f32_16x16x32_bf16 v[72:75], v[176:179], v[232:235], v[72:75]
	s_setprio 0
	s_setprio 1
	v_mfma_f32_16x16x32_bf16 v[116:119], v[180:183], v[198:201], v[116:119]
	v_mfma_f32_16x16x32_bf16 v[112:115], v[190:193], v[198:201], v[112:115]
	v_mfma_f32_16x16x32_bf16 v[100:103], v[180:183], v[206:209], v[100:103]
	v_mfma_f32_16x16x32_bf16 v[96:99], v[190:193], v[206:209], v[96:99]
	v_mfma_f32_16x16x32_bf16 v[84:87], v[180:183], v[214:217], v[84:87]
	v_mfma_f32_16x16x32_bf16 v[80:83], v[190:193], v[214:217], v[80:83]
	v_mfma_f32_16x16x32_bf16 v[68:71], v[180:183], v[228:231], v[68:71]
	v_mfma_f32_16x16x32_bf16 v[64:67], v[190:193], v[228:231], v[64:67]
	v_mfma_f32_16x16x32_bf16 v[116:119], v[186:189], v[202:205], v[116:119]
	v_mfma_f32_16x16x32_bf16 v[112:115], v[194:197], v[202:205], v[112:115]
	v_mfma_f32_16x16x32_bf16 v[100:103], v[186:189], v[210:213], v[100:103]
	v_mfma_f32_16x16x32_bf16 v[96:99], v[194:197], v[210:213], v[96:99]
	v_mfma_f32_16x16x32_bf16 v[84:87], v[186:189], v[224:227], v[84:87]
	v_mfma_f32_16x16x32_bf16 v[80:83], v[194:197], v[224:227], v[80:83]
	v_mfma_f32_16x16x32_bf16 v[68:71], v[186:189], v[232:235], v[68:71]
	v_mfma_f32_16x16x32_bf16 v[64:67], v[194:197], v[232:235], v[64:67]
	s_setprio 0
	s_barrier
	s_add_i32 s13, s37, s31
	v_lshl_add_u64 v[160:161], s[16:17], 0, v[130:131]
	s_mov_b32 m0, s13
	ds_read_b128 v[198:201], v170 offset:16384
	ds_read_b128 v[202:205], v170 offset:17408
	ds_read_b128 v[206:209], v170 offset:18432
	ds_read_b128 v[210:213], v170 offset:19456
	ds_read_b128 v[214:217], v170 offset:20480
	ds_read_b128 v[224:227], v170 offset:21504
	ds_read_b128 v[228:231], v170 offset:22528
	ds_read_b128 v[232:235], v170 offset:23552
	global_load_lds_dwordx4 v[160:161], off
	s_add_i32 m0, s13, 0x2000
	v_lshl_add_u64 v[236:237], s[16:17], 0, v[134:135]
	s_add_u32 s16, s16, s74
	s_addc_u32 s17, s17, s75
	s_add_i32 s13, s38, s31
	global_load_lds_dwordx4 v[236:237], off
	v_lshl_add_u64 v[238:239], s[16:17], 0, v[130:131]
	s_mov_b32 m0, s13
	v_lshl_add_u64 v[240:241], s[16:17], 0, v[134:135]
	global_load_lds_dwordx4 v[238:239], off
	s_add_i32 m0, s13, 0x2000
	v_lshl_add_u64 v[242:243], s[8:9], 0, v[128:129]
	global_load_lds_dwordx4 v[240:241], off
	v_lshl_add_u64 v[244:245], s[8:9], 0, v[132:133]
	s_waitcnt vmcnt(6)
	s_waitcnt lgkmcnt(0)
	s_barrier
	s_setprio 1
	s_waitcnt lgkmcnt(0)
	v_mfma_f32_16x16x32_bf16 v[60:63], v[152:155], v[198:201], v[60:63]
	v_mfma_f32_16x16x32_bf16 v[56:59], v[172:175], v[198:201], v[56:59]
	v_mfma_f32_16x16x32_bf16 v[44:47], v[152:155], v[206:209], v[44:47]
	v_mfma_f32_16x16x32_bf16 v[40:43], v[172:175], v[206:209], v[40:43]
	v_mfma_f32_16x16x32_bf16 v[28:31], v[152:155], v[214:217], v[28:31]
	v_mfma_f32_16x16x32_bf16 v[24:27], v[172:175], v[214:217], v[24:27]
	v_mfma_f32_16x16x32_bf16 v[12:15], v[152:155], v[228:231], v[12:15]
	v_mfma_f32_16x16x32_bf16 v[8:11], v[172:175], v[228:231], v[8:11]
	v_mfma_f32_16x16x32_bf16 v[60:63], v[156:159], v[202:205], v[60:63]
	v_mfma_f32_16x16x32_bf16 v[56:59], v[176:179], v[202:205], v[56:59]
	v_mfma_f32_16x16x32_bf16 v[44:47], v[156:159], v[210:213], v[44:47]
	v_mfma_f32_16x16x32_bf16 v[40:43], v[176:179], v[210:213], v[40:43]
	v_mfma_f32_16x16x32_bf16 v[28:31], v[156:159], v[224:227], v[28:31]
	v_mfma_f32_16x16x32_bf16 v[24:27], v[176:179], v[224:227], v[24:27]
	v_mfma_f32_16x16x32_bf16 v[12:15], v[156:159], v[232:235], v[12:15]
	v_mfma_f32_16x16x32_bf16 v[8:11], v[176:179], v[232:235], v[8:11]
	s_setprio 0
	s_setprio 1
	v_mfma_f32_16x16x32_bf16 v[52:55], v[180:183], v[198:201], v[52:55]
	v_mfma_f32_16x16x32_bf16 v[48:51], v[190:193], v[198:201], v[48:51]
	v_mfma_f32_16x16x32_bf16 v[36:39], v[180:183], v[206:209], v[36:39]
	v_mfma_f32_16x16x32_bf16 v[32:35], v[190:193], v[206:209], v[32:35]
	v_mfma_f32_16x16x32_bf16 v[20:23], v[180:183], v[214:217], v[20:23]
	v_mfma_f32_16x16x32_bf16 v[16:19], v[190:193], v[214:217], v[16:19]
	v_mfma_f32_16x16x32_bf16 v[4:7], v[180:183], v[228:231], v[4:7]
	v_mfma_f32_16x16x32_bf16 v[0:3], v[190:193], v[228:231], v[0:3]
	v_mfma_f32_16x16x32_bf16 v[52:55], v[186:189], v[202:205], v[52:55]
	v_mfma_f32_16x16x32_bf16 v[48:51], v[194:197], v[202:205], v[48:51]
	v_mfma_f32_16x16x32_bf16 v[36:39], v[186:189], v[210:213], v[36:39]
	v_mfma_f32_16x16x32_bf16 v[32:35], v[194:197], v[210:213], v[32:35]
	v_mfma_f32_16x16x32_bf16 v[20:23], v[186:189], v[224:227], v[20:23]
	v_mfma_f32_16x16x32_bf16 v[16:19], v[194:197], v[224:227], v[16:19]
	v_mfma_f32_16x16x32_bf16 v[4:7], v[186:189], v[232:235], v[4:7]
	v_mfma_f32_16x16x32_bf16 v[0:3], v[194:197], v[232:235], v[0:3]
	s_setprio 0
	s_barrier
	s_add_i32 s13, 0, 0x18000
	v_add_u32_e32 v136, s13, v143
	s_add_i32 s16, 0, 0x1c000
	ds_read_b128 v[152:155], v136
	ds_read_b128 v[156:159], v136 offset:1024
	ds_read_b128 v[172:175], v136 offset:2048
	ds_read_b128 v[176:179], v136 offset:3072
	v_add_u32_e32 v136, s16, v143
	ds_read_b128 v[180:183], v136
	ds_read_b128 v[186:189], v136 offset:1024
	ds_read_b128 v[190:193], v136 offset:2048
	ds_read_b128 v[194:197], v136 offset:3072
	s_add_u32 s8, s8, s74
	s_addc_u32 s9, s9, s75
	s_mov_b32 m0, s90
	s_nop 0
	global_load_lds_dwordx4 v[242:243], off
	s_mov_b32 m0, s91
	s_nop 0
	global_load_lds_dwordx4 v[244:245], off
	s_mov_b32 m0, s78
	v_lshl_add_u64 v[246:247], s[8:9], 0, v[128:129]
	ds_read_b128 v[198:201], v170 offset:32768
	ds_read_b128 v[202:205], v170 offset:33792
	ds_read_b128 v[206:209], v170 offset:34816
	ds_read_b128 v[210:213], v170 offset:35840
	ds_read_b128 v[214:217], v170 offset:36864
	ds_read_b128 v[224:227], v170 offset:37888
	ds_read_b128 v[228:231], v170 offset:38912
	ds_read_b128 v[232:235], v170 offset:39936
	global_load_lds_dwordx4 v[246:247], off
	v_lshl_add_u64 v[246:247], s[8:9], 0, v[132:133]
	s_mov_b32 m0, s79
	s_nop 0
	global_load_lds_dwordx4 v[246:247], off
	s_waitcnt vmcnt(8)
	s_waitcnt lgkmcnt(0)
	s_barrier
	s_setprio 1
	s_waitcnt lgkmcnt(0)
	v_mfma_f32_16x16x32_bf16 v[124:127], v[152:155], v[198:201], v[124:127]
	v_mfma_f32_16x16x32_bf16 v[120:123], v[172:175], v[198:201], v[120:123]
	v_mfma_f32_16x16x32_bf16 v[108:111], v[152:155], v[206:209], v[108:111]
	v_mfma_f32_16x16x32_bf16 v[104:107], v[172:175], v[206:209], v[104:107]
	v_mfma_f32_16x16x32_bf16 v[92:95], v[152:155], v[214:217], v[92:95]
	v_mfma_f32_16x16x32_bf16 v[88:91], v[172:175], v[214:217], v[88:91]
	v_mfma_f32_16x16x32_bf16 v[76:79], v[152:155], v[228:231], v[76:79]
	v_mfma_f32_16x16x32_bf16 v[72:75], v[172:175], v[228:231], v[72:75]
	v_mfma_f32_16x16x32_bf16 v[124:127], v[156:159], v[202:205], v[124:127]
	v_mfma_f32_16x16x32_bf16 v[120:123], v[176:179], v[202:205], v[120:123]
	v_mfma_f32_16x16x32_bf16 v[108:111], v[156:159], v[210:213], v[108:111]
	v_mfma_f32_16x16x32_bf16 v[104:107], v[176:179], v[210:213], v[104:107]
	v_mfma_f32_16x16x32_bf16 v[92:95], v[156:159], v[224:227], v[92:95]
	v_mfma_f32_16x16x32_bf16 v[88:91], v[176:179], v[224:227], v[88:91]
	v_mfma_f32_16x16x32_bf16 v[76:79], v[156:159], v[232:235], v[76:79]
	v_mfma_f32_16x16x32_bf16 v[72:75], v[176:179], v[232:235], v[72:75]
	s_setprio 0
	s_setprio 1
	v_mfma_f32_16x16x32_bf16 v[116:119], v[180:183], v[198:201], v[116:119]
	v_mfma_f32_16x16x32_bf16 v[112:115], v[190:193], v[198:201], v[112:115]
	v_mfma_f32_16x16x32_bf16 v[100:103], v[180:183], v[206:209], v[100:103]
	v_mfma_f32_16x16x32_bf16 v[96:99], v[190:193], v[206:209], v[96:99]
	v_mfma_f32_16x16x32_bf16 v[84:87], v[180:183], v[214:217], v[84:87]
	v_mfma_f32_16x16x32_bf16 v[80:83], v[190:193], v[214:217], v[80:83]
	v_mfma_f32_16x16x32_bf16 v[68:71], v[180:183], v[228:231], v[68:71]
	v_mfma_f32_16x16x32_bf16 v[64:67], v[190:193], v[228:231], v[64:67]
	v_mfma_f32_16x16x32_bf16 v[116:119], v[186:189], v[202:205], v[116:119]
	v_mfma_f32_16x16x32_bf16 v[112:115], v[194:197], v[202:205], v[112:115]
	v_mfma_f32_16x16x32_bf16 v[100:103], v[186:189], v[210:213], v[100:103]
	v_mfma_f32_16x16x32_bf16 v[96:99], v[194:197], v[210:213], v[96:99]
	v_mfma_f32_16x16x32_bf16 v[84:87], v[186:189], v[224:227], v[84:87]
	v_mfma_f32_16x16x32_bf16 v[80:83], v[194:197], v[224:227], v[80:83]
	v_mfma_f32_16x16x32_bf16 v[68:71], v[186:189], v[232:235], v[68:71]
	v_mfma_f32_16x16x32_bf16 v[64:67], v[194:197], v[232:235], v[64:67]
	s_setprio 0
	s_barrier
	s_add_i32 s8, s13, s31
	v_lshl_add_u64 v[160:161], v[160:161], 0, s[92:93]
	s_mov_b32 m0, s8
	ds_read_b128 v[198:201], v170 offset:49152
	ds_read_b128 v[202:205], v170 offset:50176
	ds_read_b128 v[206:209], v170 offset:51200
	ds_read_b128 v[210:213], v170 offset:52224
	ds_read_b128 v[214:217], v170 offset:53248
	ds_read_b128 v[224:227], v170 offset:54272
	ds_read_b128 v[228:231], v170 offset:55296
	ds_read_b128 v[232:235], v170 offset:56320
	global_load_lds_dwordx4 v[160:161], off
	v_lshl_add_u64 v[160:161], v[236:237], 0, s[92:93]
	s_add_i32 m0, s8, 0x2000
	s_add_i32 s8, s16, s31
	global_load_lds_dwordx4 v[160:161], off
	v_lshl_add_u64 v[160:161], v[238:239], 0, s[92:93]
	s_mov_b32 m0, s8
	s_nop 0
	global_load_lds_dwordx4 v[160:161], off
	v_lshl_add_u64 v[160:161], v[240:241], 0, s[92:93]
	s_add_i32 m0, s8, 0x2000
	s_nop 0
	global_load_lds_dwordx4 v[160:161], off
	s_waitcnt vmcnt(6)
	s_waitcnt lgkmcnt(0)
	s_barrier
	s_setprio 1
	s_waitcnt lgkmcnt(0)
	v_mfma_f32_16x16x32_bf16 v[60:63], v[152:155], v[198:201], v[60:63]
	v_mfma_f32_16x16x32_bf16 v[56:59], v[172:175], v[198:201], v[56:59]
	v_mfma_f32_16x16x32_bf16 v[44:47], v[152:155], v[206:209], v[44:47]
	v_mfma_f32_16x16x32_bf16 v[40:43], v[172:175], v[206:209], v[40:43]
	v_mfma_f32_16x16x32_bf16 v[28:31], v[152:155], v[214:217], v[28:31]
	v_mfma_f32_16x16x32_bf16 v[24:27], v[172:175], v[214:217], v[24:27]
	v_mfma_f32_16x16x32_bf16 v[12:15], v[152:155], v[228:231], v[12:15]
	v_mfma_f32_16x16x32_bf16 v[8:11], v[172:175], v[228:231], v[8:11]
	v_mfma_f32_16x16x32_bf16 v[60:63], v[156:159], v[202:205], v[60:63]
	v_mfma_f32_16x16x32_bf16 v[56:59], v[176:179], v[202:205], v[56:59]
	v_mfma_f32_16x16x32_bf16 v[44:47], v[156:159], v[210:213], v[44:47]
	v_mfma_f32_16x16x32_bf16 v[40:43], v[176:179], v[210:213], v[40:43]
	v_mfma_f32_16x16x32_bf16 v[28:31], v[156:159], v[224:227], v[28:31]
	v_mfma_f32_16x16x32_bf16 v[24:27], v[176:179], v[224:227], v[24:27]
	v_mfma_f32_16x16x32_bf16 v[12:15], v[156:159], v[232:235], v[12:15]
	v_mfma_f32_16x16x32_bf16 v[8:11], v[176:179], v[232:235], v[8:11]
	s_setprio 0
	s_setprio 1
	v_mfma_f32_16x16x32_bf16 v[52:55], v[180:183], v[198:201], v[52:55]
	v_mfma_f32_16x16x32_bf16 v[48:51], v[190:193], v[198:201], v[48:51]
	v_mfma_f32_16x16x32_bf16 v[36:39], v[180:183], v[206:209], v[36:39]
	v_mfma_f32_16x16x32_bf16 v[32:35], v[190:193], v[206:209], v[32:35]
	v_mfma_f32_16x16x32_bf16 v[20:23], v[180:183], v[214:217], v[20:23]
	v_mfma_f32_16x16x32_bf16 v[16:19], v[190:193], v[214:217], v[16:19]
	v_mfma_f32_16x16x32_bf16 v[4:7], v[180:183], v[228:231], v[4:7]
	v_mfma_f32_16x16x32_bf16 v[0:3], v[190:193], v[228:231], v[0:3]
	v_mfma_f32_16x16x32_bf16 v[52:55], v[186:189], v[202:205], v[52:55]
	v_mfma_f32_16x16x32_bf16 v[48:51], v[194:197], v[202:205], v[48:51]
	v_mfma_f32_16x16x32_bf16 v[36:39], v[186:189], v[210:213], v[36:39]
	v_mfma_f32_16x16x32_bf16 v[32:35], v[194:197], v[210:213], v[32:35]
	v_mfma_f32_16x16x32_bf16 v[20:23], v[186:189], v[224:227], v[20:23]
	v_mfma_f32_16x16x32_bf16 v[16:19], v[194:197], v[224:227], v[16:19]
	v_mfma_f32_16x16x32_bf16 v[4:7], v[186:189], v[232:235], v[4:7]
	v_mfma_f32_16x16x32_bf16 v[0:3], v[194:197], v[232:235], v[0:3]
	s_setprio 0
	s_barrier
	s_add_u32 s6, s6, 0x100
	s_addc_u32 s7, s7, 0
	s_add_u32 s10, s10, 0x100
	s_addc_u32 s11, s11, 0
	s_cmp_ge_i32 s12, s36
	s_mov_b32 s8, s12
	s_cbranch_scc0 .LBB0_207
	s_branch .LBB0_208

.LBB0_631:
	s_mov_b64 s[40:41], 0x80
	v_lshl_add_u64 v[0:1], v[0:1], 0, s[40:41]
	s_add_i32 m0, s3, 0x18000
	s_waitcnt vmcnt(2)
	s_barrier
	global_load_lds_dwordx4 v[0:1], off
	v_lshl_add_u64 v[0:1], v[4:5], 0, s[40:41]
	s_add_i32 m0, s3, 0x1a000
	s_add_i32 s47, s3, 0x8000
	global_load_lds_dwordx4 v[0:1], off
	v_mov_b32_e32 v232, v8
	v_mov_b32_e32 v233, v9
	v_mov_b32_e32 v234, v10
	v_mov_b32_e32 v235, v11
	v_lshl_add_u64 v[0:1], v[8:9], 0, s[40:41]
	s_mov_b32 m0, s47
	s_add_i32 s48, s3, 0xa000
	global_load_lds_dwordx4 v[0:1], off
	v_lshl_add_u64 v[0:1], v[10:11], 0, s[40:41]
	s_mov_b32 m0, s48
	s_lshr_b32 s5, s5, 26
	global_load_lds_dwordx4 v[0:1], off
	v_lshl_add_u64 v[0:1], v[2:3], 0, s[40:41]
	s_add_i32 m0, s3, 0x1c000
	s_add_i32 s5, s4, s5
	global_load_lds_dwordx4 v[0:1], off
	v_lshl_add_u64 v[0:1], v[6:7], 0, s[40:41]
	s_add_i32 m0, s3, 0x1e000
	v_and_b32_e32 v20, 15, v12
	global_load_lds_dwordx4 v[0:1], off
	s_ashr_i32 s45, s5, 6
	v_readlane_b32 s5, v248, 17
	v_and_b32_e32 v23, 48, v12
	v_and_b32_e32 v19, 0xfffffc00, v19
	v_or_b32_e32 v150, s5, v20
	v_lshlrev_b32_e32 v22, 6, v150
	s_movk_i32 s5, 0x3c0
	v_and_or_b32 v22, v22, s5, v23
	v_lshlrev_b32_e32 v25, 2, v150
	v_lshl_or_b32 v20, v20, 6, v23
	v_lshlrev_b32_e32 v23, 2, v12
	s_cmp_gt_i32 s4, 63
	v_add_u32_e32 v0, v15, v13
	v_ashrrev_i32_e32 v21, 1, v12
	v_add_u32_e32 v24, s89, v19
	v_and_b32_e32 v25, 32, v25
	v_lshl_add_u32 v19, s29, 12, v19
	v_and_b32_e32 v23, 32, v23
	s_waitcnt vmcnt(6)
	s_cselect_b64 s[4:5], -1, 0
	v_add_lshl_u32 v136, v0, v14, 1
	v_add_u32_e32 v0, v18, v16
	v_and_b32_e32 v21, -8, v21
	v_bitop3_b32 v22, v22, v24, v25 bitop3:0xde
	v_bitop3_b32 v151, v20, v19, v23 bitop3:0xde
	v_readlane_b32 s6, v248, 18
	v_lshl_add_u64 v[138:139], s[18:19], 0, v[136:137]
	v_add_lshl_u32 v136, v0, v17, 1
	v_cndmask_b32_e64 v0, 0, 1, s[4:5]
	s_add_i32 s50, 0, 0x10000
	s_add_i32 s51, 0, 0x14000
	s_mov_b32 s46, 0x8000
	s_add_i32 s49, s45, -2
	v_add_u32_e32 v152, s6, v21
	v_cmp_gt_u32_e64 s[10:11], 16, v12
	v_lshl_add_u64 v[140:141], s[18:19], 0, v[136:137]
	v_mov_b64_e32 v[142:143], 0x210
	v_mov_b64_e32 v[144:145], 0x20f
	v_cmp_ne_u32_e64 s[4:5], 1, v0
	v_add_u32_e32 v153, s50, v151
	v_add_u32_e32 v154, s51, v151
	v_add_u32_e32 v155, 0, v22
	s_mov_b32 s52, 0
	s_barrier
	s_branch .LBB0_634

.LBB0_640:
	s_and_b64 vcc, exec, s[4:5]
	s_waitcnt lgkmcnt(0)
	s_cbranch_vccnz .Lzx642
	s_add_u32 s56, s56, 0x80
	s_addc_u32 s57, s57, 0
	s_add_u32 s62, s58, 0x100
	s_addc_u32 s63, s59, 0
	s_mov_b32 s58, 0
	ds_read_b128 v[146:149], v153
	ds_read_b128 v[156:159], v153 offset:1024
	ds_read_b128 v[160:163], v153 offset:2048
	ds_read_b128 v[164:167], v153 offset:3072
	ds_read_b128 v[168:171], v154
	ds_read_b128 v[172:175], v154 offset:1024
	ds_read_b128 v[176:179], v154 offset:2048
	ds_read_b128 v[180:183], v154 offset:3072
	s_add_i32 s64, s58, 2
	s_add_u32 s65, s56, 0x80
	s_addc_u32 s59, s57, 0
	s_cmp_eq_u32 s49, s58
	s_cselect_b32 s58, s8, s65
	s_cselect_b32 s59, s9, s59
	s_cselect_b32 s67, s43, s63
	s_cselect_b32 s66, s42, s62
	v_lshl_add_u64 v[224:225], v[232:233], 0, s[40:41]
	s_mov_b32 m0, s47
	s_nop 0
	global_load_lds_dwordx4 v[224:225], off
	v_lshl_add_u64 v[224:225], v[234:235], 0, s[40:41]
	s_mov_b32 m0, s48
	s_nop 0
	global_load_lds_dwordx4 v[224:225], off
	v_lshl_add_u64 v[224:225], s[56:57], 0, v[138:139]
	s_add_i32 m0, s3, 0xc000
	ds_read_b128 v[186:189], v155
	ds_read_b128 v[190:193], v155 offset:1024
	ds_read_b128 v[194:197], v155 offset:2048
	ds_read_b128 v[198:201], v155 offset:3072
	ds_read_b128 v[202:205], v155 offset:4096
	ds_read_b128 v[206:209], v155 offset:5120
	ds_read_b128 v[210:213], v155 offset:6144
	ds_read_b128 v[214:217], v155 offset:7168
	global_load_lds_dwordx4 v[224:225], off
	v_lshl_add_u64 v[224:225], s[56:57], 0, v[140:141]
	s_add_i32 m0, s3, 0xe000
	s_nop 0
	global_load_lds_dwordx4 v[224:225], off
	s_waitcnt vmcnt(8)
	s_waitcnt lgkmcnt(0)
	s_barrier
	s_setprio 1
	s_waitcnt lgkmcnt(0)
	v_mfma_f32_16x16x32_bf16 v[124:127], v[146:149], v[186:189], 0
	v_mfma_f32_16x16x32_bf16 v[120:123], v[160:163], v[186:189], 0
	v_mfma_f32_16x16x32_bf16 v[108:111], v[146:149], v[194:197], 0
	v_mfma_f32_16x16x32_bf16 v[104:107], v[160:163], v[194:197], 0
	v_mfma_f32_16x16x32_bf16 v[92:95], v[146:149], v[202:205], 0
	v_mfma_f32_16x16x32_bf16 v[88:91], v[160:163], v[202:205], 0
	v_mfma_f32_16x16x32_bf16 v[76:79], v[146:149], v[210:213], 0
	v_mfma_f32_16x16x32_bf16 v[72:75], v[160:163], v[210:213], 0
	v_mfma_f32_16x16x32_bf16 v[124:127], v[156:159], v[190:193], v[124:127]
	v_mfma_f32_16x16x32_bf16 v[120:123], v[164:167], v[190:193], v[120:123]
	v_mfma_f32_16x16x32_bf16 v[108:111], v[156:159], v[198:201], v[108:111]
	v_mfma_f32_16x16x32_bf16 v[104:107], v[164:167], v[198:201], v[104:107]
	v_mfma_f32_16x16x32_bf16 v[92:95], v[156:159], v[206:209], v[92:95]
	v_mfma_f32_16x16x32_bf16 v[88:91], v[164:167], v[206:209], v[88:91]
	v_mfma_f32_16x16x32_bf16 v[76:79], v[156:159], v[214:217], v[76:79]
	v_mfma_f32_16x16x32_bf16 v[72:75], v[164:167], v[214:217], v[72:75]
	s_setprio 0
	s_setprio 1
	v_mfma_f32_16x16x32_bf16 v[116:119], v[168:171], v[186:189], 0
	v_mfma_f32_16x16x32_bf16 v[112:115], v[176:179], v[186:189], 0
	v_mfma_f32_16x16x32_bf16 v[100:103], v[168:171], v[194:197], 0
	v_mfma_f32_16x16x32_bf16 v[96:99], v[176:179], v[194:197], 0
	v_mfma_f32_16x16x32_bf16 v[84:87], v[168:171], v[202:205], 0
	v_mfma_f32_16x16x32_bf16 v[80:83], v[176:179], v[202:205], 0
	v_mfma_f32_16x16x32_bf16 v[68:71], v[168:171], v[210:213], 0
	v_mfma_f32_16x16x32_bf16 v[64:67], v[176:179], v[210:213], 0
	v_mfma_f32_16x16x32_bf16 v[116:119], v[172:175], v[190:193], v[116:119]
	v_mfma_f32_16x16x32_bf16 v[112:115], v[180:183], v[190:193], v[112:115]
	v_mfma_f32_16x16x32_bf16 v[100:103], v[172:175], v[198:201], v[100:103]
	v_mfma_f32_16x16x32_bf16 v[96:99], v[180:183], v[198:201], v[96:99]
	v_mfma_f32_16x16x32_bf16 v[84:87], v[172:175], v[206:209], v[84:87]
	v_mfma_f32_16x16x32_bf16 v[80:83], v[180:183], v[206:209], v[80:83]
	v_mfma_f32_16x16x32_bf16 v[68:71], v[172:175], v[214:217], v[68:71]
	v_mfma_f32_16x16x32_bf16 v[64:67], v[180:183], v[214:217], v[64:67]
	s_setprio 0
	s_barrier
	s_add_i32 s65, s50, s31
	v_lshl_add_u64 v[224:225], s[66:67], 0, v[130:131]
	s_mov_b32 m0, s65
	ds_read_b128 v[186:189], v155 offset:16384
	ds_read_b128 v[190:193], v155 offset:17408
	ds_read_b128 v[194:197], v155 offset:18432
	ds_read_b128 v[198:201], v155 offset:19456
	ds_read_b128 v[202:205], v155 offset:20480
	ds_read_b128 v[206:209], v155 offset:21504
	ds_read_b128 v[210:213], v155 offset:22528
	ds_read_b128 v[214:217], v155 offset:23552
	global_load_lds_dwordx4 v[224:225], off
	s_add_i32 m0, s65, 0x2000
	v_lshl_add_u64 v[226:227], s[66:67], 0, v[134:135]
	s_add_u32 s66, s66, s18
	s_addc_u32 s67, s67, s19
	s_add_i32 s65, s51, s31
	global_load_lds_dwordx4 v[226:227], off
	v_lshl_add_u64 v[228:229], s[66:67], 0, v[130:131]
	s_mov_b32 m0, s65
	v_lshl_add_u64 v[230:231], s[66:67], 0, v[134:135]
	global_load_lds_dwordx4 v[228:229], off
	s_add_i32 m0, s65, 0x2000
	v_lshl_add_u64 v[232:233], s[58:59], 0, v[128:129]
	global_load_lds_dwordx4 v[230:231], off
	v_lshl_add_u64 v[234:235], s[58:59], 0, v[132:133]
	s_waitcnt vmcnt(6)
	s_waitcnt lgkmcnt(0)
	s_barrier
	s_setprio 1
	s_waitcnt lgkmcnt(0)
	v_mfma_f32_16x16x32_bf16 v[60:63], v[146:149], v[186:189], 0
	v_mfma_f32_16x16x32_bf16 v[56:59], v[160:163], v[186:189], 0
	v_mfma_f32_16x16x32_bf16 v[44:47], v[146:149], v[194:197], 0
	v_mfma_f32_16x16x32_bf16 v[40:43], v[160:163], v[194:197], 0
	v_mfma_f32_16x16x32_bf16 v[28:31], v[146:149], v[202:205], 0
	v_mfma_f32_16x16x32_bf16 v[24:27], v[160:163], v[202:205], 0
	v_mfma_f32_16x16x32_bf16 v[12:15], v[146:149], v[210:213], 0
	v_mfma_f32_16x16x32_bf16 v[8:11], v[160:163], v[210:213], 0
	v_mfma_f32_16x16x32_bf16 v[60:63], v[156:159], v[190:193], v[60:63]
	v_mfma_f32_16x16x32_bf16 v[56:59], v[164:167], v[190:193], v[56:59]
	v_mfma_f32_16x16x32_bf16 v[44:47], v[156:159], v[198:201], v[44:47]
	v_mfma_f32_16x16x32_bf16 v[40:43], v[164:167], v[198:201], v[40:43]
	v_mfma_f32_16x16x32_bf16 v[28:31], v[156:159], v[206:209], v[28:31]
	v_mfma_f32_16x16x32_bf16 v[24:27], v[164:167], v[206:209], v[24:27]
	v_mfma_f32_16x16x32_bf16 v[12:15], v[156:159], v[214:217], v[12:15]
	v_mfma_f32_16x16x32_bf16 v[8:11], v[164:167], v[214:217], v[8:11]
	s_setprio 0
	s_setprio 1
	v_mfma_f32_16x16x32_bf16 v[52:55], v[168:171], v[186:189], 0
	v_mfma_f32_16x16x32_bf16 v[48:51], v[176:179], v[186:189], 0
	v_mfma_f32_16x16x32_bf16 v[36:39], v[168:171], v[194:197], 0
	v_mfma_f32_16x16x32_bf16 v[32:35], v[176:179], v[194:197], 0
	v_mfma_f32_16x16x32_bf16 v[20:23], v[168:171], v[202:205], 0
	v_mfma_f32_16x16x32_bf16 v[16:19], v[176:179], v[202:205], 0
	v_mfma_f32_16x16x32_bf16 v[4:7], v[168:171], v[210:213], 0
	v_mfma_f32_16x16x32_bf16 v[0:3], v[176:179], v[210:213], 0
	v_mfma_f32_16x16x32_bf16 v[52:55], v[172:175], v[190:193], v[52:55]
	v_mfma_f32_16x16x32_bf16 v[48:51], v[180:183], v[190:193], v[48:51]
	v_mfma_f32_16x16x32_bf16 v[36:39], v[172:175], v[198:201], v[36:39]
	v_mfma_f32_16x16x32_bf16 v[32:35], v[180:183], v[198:201], v[32:35]
	v_mfma_f32_16x16x32_bf16 v[20:23], v[172:175], v[206:209], v[20:23]
	v_mfma_f32_16x16x32_bf16 v[16:19], v[180:183], v[206:209], v[16:19]
	v_mfma_f32_16x16x32_bf16 v[4:7], v[172:175], v[214:217], v[4:7]
	v_mfma_f32_16x16x32_bf16 v[0:3], v[180:183], v[214:217], v[0:3]
	s_setprio 0
	s_barrier
	s_add_i32 s65, 0, 0x18000
	v_add_u32_e32 v136, s65, v151
	s_add_i32 s66, 0, 0x1c000
	ds_read_b128 v[146:149], v136
	ds_read_b128 v[156:159], v136 offset:1024
	ds_read_b128 v[160:163], v136 offset:2048
	ds_read_b128 v[164:167], v136 offset:3072
	v_add_u32_e32 v136, s66, v151
	ds_read_b128 v[168:171], v136
	ds_read_b128 v[172:175], v136 offset:1024
	ds_read_b128 v[176:179], v136 offset:2048
	ds_read_b128 v[180:183], v136 offset:3072
	s_add_u32 s58, s58, s18
	s_addc_u32 s59, s59, s19
	s_mov_b32 m0, s3
	s_nop 0
	global_load_lds_dwordx4 v[232:233], off
	s_mov_b32 m0, s28
	s_nop 0
	global_load_lds_dwordx4 v[234:235], off
	s_mov_b32 m0, s33
	v_lshl_add_u64 v[236:237], s[58:59], 0, v[128:129]
	ds_read_b128 v[186:189], v155 offset:32768
	ds_read_b128 v[190:193], v155 offset:33792
	ds_read_b128 v[194:197], v155 offset:34816
	ds_read_b128 v[198:201], v155 offset:35840
	ds_read_b128 v[202:205], v155 offset:36864
	ds_read_b128 v[206:209], v155 offset:37888
	ds_read_b128 v[210:213], v155 offset:38912
	ds_read_b128 v[214:217], v155 offset:39936
	global_load_lds_dwordx4 v[236:237], off
	v_lshl_add_u64 v[236:237], s[58:59], 0, v[132:133]
	s_mov_b32 m0, s44
	s_nop 0
	global_load_lds_dwordx4 v[236:237], off
	s_waitcnt vmcnt(8)
	s_waitcnt lgkmcnt(0)
	s_barrier
	s_setprio 1
	s_waitcnt lgkmcnt(0)
	v_mfma_f32_16x16x32_bf16 v[124:127], v[146:149], v[186:189], v[124:127]
	v_mfma_f32_16x16x32_bf16 v[120:123], v[160:163], v[186:189], v[120:123]
	v_mfma_f32_16x16x32_bf16 v[108:111], v[146:149], v[194:197], v[108:111]
	v_mfma_f32_16x16x32_bf16 v[104:107], v[160:163], v[194:197], v[104:107]
	v_mfma_f32_16x16x32_bf16 v[92:95], v[146:149], v[202:205], v[92:95]
	v_mfma_f32_16x16x32_bf16 v[88:91], v[160:163], v[202:205], v[88:91]
	v_mfma_f32_16x16x32_bf16 v[76:79], v[146:149], v[210:213], v[76:79]
	v_mfma_f32_16x16x32_bf16 v[72:75], v[160:163], v[210:213], v[72:75]
	v_mfma_f32_16x16x32_bf16 v[124:127], v[156:159], v[190:193], v[124:127]
	v_mfma_f32_16x16x32_bf16 v[120:123], v[164:167], v[190:193], v[120:123]
	v_mfma_f32_16x16x32_bf16 v[108:111], v[156:159], v[198:201], v[108:111]
	v_mfma_f32_16x16x32_bf16 v[104:107], v[164:167], v[198:201], v[104:107]
	v_mfma_f32_16x16x32_bf16 v[92:95], v[156:159], v[206:209], v[92:95]
	v_mfma_f32_16x16x32_bf16 v[88:91], v[164:167], v[206:209], v[88:91]
	v_mfma_f32_16x16x32_bf16 v[76:79], v[156:159], v[214:217], v[76:79]
	v_mfma_f32_16x16x32_bf16 v[72:75], v[164:167], v[214:217], v[72:75]
	s_setprio 0
	s_setprio 1
	v_mfma_f32_16x16x32_bf16 v[116:119], v[168:171], v[186:189], v[116:119]
	v_mfma_f32_16x16x32_bf16 v[112:115], v[176:179], v[186:189], v[112:115]
	v_mfma_f32_16x16x32_bf16 v[100:103], v[168:171], v[194:197], v[100:103]
	v_mfma_f32_16x16x32_bf16 v[96:99], v[176:179], v[194:197], v[96:99]
	v_mfma_f32_16x16x32_bf16 v[84:87], v[168:171], v[202:205], v[84:87]
	v_mfma_f32_16x16x32_bf16 v[80:83], v[176:179], v[202:205], v[80:83]
	v_mfma_f32_16x16x32_bf16 v[68:71], v[168:171], v[210:213], v[68:71]
	v_mfma_f32_16x16x32_bf16 v[64:67], v[176:179], v[210:213], v[64:67]
	v_mfma_f32_16x16x32_bf16 v[116:119], v[172:175], v[190:193], v[116:119]
	v_mfma_f32_16x16x32_bf16 v[112:115], v[180:183], v[190:193], v[112:115]
	v_mfma_f32_16x16x32_bf16 v[100:103], v[172:175], v[198:201], v[100:103]
	v_mfma_f32_16x16x32_bf16 v[96:99], v[180:183], v[198:201], v[96:99]
	v_mfma_f32_16x16x32_bf16 v[84:87], v[172:175], v[206:209], v[84:87]
	v_mfma_f32_16x16x32_bf16 v[80:83], v[180:183], v[206:209], v[80:83]
	v_mfma_f32_16x16x32_bf16 v[68:71], v[172:175], v[214:217], v[68:71]
	v_mfma_f32_16x16x32_bf16 v[64:67], v[180:183], v[214:217], v[64:67]
	s_setprio 0
	s_barrier
	s_add_i32 s58, s65, s31
	v_lshl_add_u64 v[224:225], v[224:225], 0, s[40:41]
	s_mov_b32 m0, s58
	ds_read_b128 v[186:189], v155 offset:49152
	ds_read_b128 v[190:193], v155 offset:50176
	ds_read_b128 v[194:197], v155 offset:51200
	ds_read_b128 v[198:201], v155 offset:52224
	ds_read_b128 v[202:205], v155 offset:53248
	ds_read_b128 v[206:209], v155 offset:54272
	ds_read_b128 v[210:213], v155 offset:55296
	ds_read_b128 v[214:217], v155 offset:56320
	global_load_lds_dwordx4 v[224:225], off
	v_lshl_add_u64 v[224:225], v[226:227], 0, s[40:41]
	s_add_i32 m0, s58, 0x2000
	s_add_i32 s58, s66, s31
	global_load_lds_dwordx4 v[224:225], off
	v_lshl_add_u64 v[224:225], v[228:229], 0, s[40:41]
	s_mov_b32 m0, s58
	s_nop 0
	global_load_lds_dwordx4 v[224:225], off
	v_lshl_add_u64 v[224:225], v[230:231], 0, s[40:41]
	s_add_i32 m0, s58, 0x2000
	s_nop 0
	global_load_lds_dwordx4 v[224:225], off
	s_waitcnt vmcnt(6)
	s_waitcnt lgkmcnt(0)
	s_barrier
	s_setprio 1
	s_waitcnt lgkmcnt(0)
	v_mfma_f32_16x16x32_bf16 v[60:63], v[146:149], v[186:189], v[60:63]
	v_mfma_f32_16x16x32_bf16 v[56:59], v[160:163], v[186:189], v[56:59]
	v_mfma_f32_16x16x32_bf16 v[44:47], v[146:149], v[194:197], v[44:47]
	v_mfma_f32_16x16x32_bf16 v[40:43], v[160:163], v[194:197], v[40:43]
	v_mfma_f32_16x16x32_bf16 v[28:31], v[146:149], v[202:205], v[28:31]
	v_mfma_f32_16x16x32_bf16 v[24:27], v[160:163], v[202:205], v[24:27]
	v_mfma_f32_16x16x32_bf16 v[12:15], v[146:149], v[210:213], v[12:15]
	v_mfma_f32_16x16x32_bf16 v[8:11], v[160:163], v[210:213], v[8:11]
	v_mfma_f32_16x16x32_bf16 v[60:63], v[156:159], v[190:193], v[60:63]
	v_mfma_f32_16x16x32_bf16 v[56:59], v[164:167], v[190:193], v[56:59]
	v_mfma_f32_16x16x32_bf16 v[44:47], v[156:159], v[198:201], v[44:47]
	v_mfma_f32_16x16x32_bf16 v[40:43], v[164:167], v[198:201], v[40:43]
	v_mfma_f32_16x16x32_bf16 v[28:31], v[156:159], v[206:209], v[28:31]
	v_mfma_f32_16x16x32_bf16 v[24:27], v[164:167], v[206:209], v[24:27]
	v_mfma_f32_16x16x32_bf16 v[12:15], v[156:159], v[214:217], v[12:15]
	v_mfma_f32_16x16x32_bf16 v[8:11], v[164:167], v[214:217], v[8:11]
	s_setprio 0
	s_setprio 1
	v_mfma_f32_16x16x32_bf16 v[52:55], v[168:171], v[186:189], v[52:55]
	v_mfma_f32_16x16x32_bf16 v[48:51], v[176:179], v[186:189], v[48:51]
	v_mfma_f32_16x16x32_bf16 v[36:39], v[168:171], v[194:197], v[36:39]
	v_mfma_f32_16x16x32_bf16 v[32:35], v[176:179], v[194:197], v[32:35]
	v_mfma_f32_16x16x32_bf16 v[20:23], v[168:171], v[202:205], v[20:23]
	v_mfma_f32_16x16x32_bf16 v[16:19], v[176:179], v[202:205], v[16:19]
	v_mfma_f32_16x16x32_bf16 v[4:7], v[168:171], v[210:213], v[4:7]
	v_mfma_f32_16x16x32_bf16 v[0:3], v[176:179], v[210:213], v[0:3]
	v_mfma_f32_16x16x32_bf16 v[52:55], v[172:175], v[190:193], v[52:55]
	v_mfma_f32_16x16x32_bf16 v[48:51], v[180:183], v[190:193], v[48:51]
	v_mfma_f32_16x16x32_bf16 v[36:39], v[172:175], v[198:201], v[36:39]
	v_mfma_f32_16x16x32_bf16 v[32:35], v[180:183], v[198:201], v[32:35]
	v_mfma_f32_16x16x32_bf16 v[20:23], v[172:175], v[206:209], v[20:23]
	v_mfma_f32_16x16x32_bf16 v[16:19], v[180:183], v[206:209], v[16:19]
	v_mfma_f32_16x16x32_bf16 v[4:7], v[172:175], v[214:217], v[4:7]
	v_mfma_f32_16x16x32_bf16 v[0:3], v[180:183], v[214:217], v[0:3]
	s_setprio 0
	s_barrier
	s_add_u32 s56, s56, 0x100
	s_addc_u32 s57, s57, 0
	s_add_u32 s62, s62, 0x100
	s_addc_u32 s63, s63, 0
	s_cmp_ge_i32 s64, s45
	s_mov_b32 s58, s64
	s_cbranch_scc1 .LBB0_643
.LBB0_642:
	ds_read_b128 v[146:149], v153
	ds_read_b128 v[156:159], v153 offset:1024
	ds_read_b128 v[160:163], v153 offset:2048
	ds_read_b128 v[164:167], v153 offset:3072
	ds_read_b128 v[168:171], v154
	ds_read_b128 v[172:175], v154 offset:1024
	ds_read_b128 v[176:179], v154 offset:2048
	ds_read_b128 v[180:183], v154 offset:3072
	s_add_i32 s64, s58, 2
	s_add_u32 s65, s56, 0x80
	s_addc_u32 s59, s57, 0
	s_cmp_eq_u32 s49, s58
	s_cselect_b32 s58, s8, s65
	s_cselect_b32 s59, s9, s59
	s_cselect_b32 s67, s43, s63
	s_cselect_b32 s66, s42, s62
	v_lshl_add_u64 v[224:225], v[232:233], 0, s[40:41]
	s_mov_b32 m0, s47
	s_nop 0
	global_load_lds_dwordx4 v[224:225], off
	v_lshl_add_u64 v[224:225], v[234:235], 0, s[40:41]
	s_mov_b32 m0, s48
	s_nop 0
	global_load_lds_dwordx4 v[224:225], off
	v_lshl_add_u64 v[224:225], s[56:57], 0, v[138:139]
	s_add_i32 m0, s3, 0xc000
	ds_read_b128 v[186:189], v155
	ds_read_b128 v[190:193], v155 offset:1024
	ds_read_b128 v[194:197], v155 offset:2048
	ds_read_b128 v[198:201], v155 offset:3072
	ds_read_b128 v[202:205], v155 offset:4096
	ds_read_b128 v[206:209], v155 offset:5120
	ds_read_b128 v[210:213], v155 offset:6144
	ds_read_b128 v[214:217], v155 offset:7168
	global_load_lds_dwordx4 v[224:225], off
	v_lshl_add_u64 v[224:225], s[56:57], 0, v[140:141]
	s_add_i32 m0, s3, 0xe000
	s_nop 0
	global_load_lds_dwordx4 v[224:225], off
	s_waitcnt vmcnt(8)
	s_waitcnt lgkmcnt(0)
	s_barrier
	s_setprio 1
	s_waitcnt lgkmcnt(0)
	v_mfma_f32_16x16x32_bf16 v[124:127], v[146:149], v[186:189], v[124:127]
	v_mfma_f32_16x16x32_bf16 v[120:123], v[160:163], v[186:189], v[120:123]
	v_mfma_f32_16x16x32_bf16 v[108:111], v[146:149], v[194:197], v[108:111]
	v_mfma_f32_16x16x32_bf16 v[104:107], v[160:163], v[194:197], v[104:107]
	v_mfma_f32_16x16x32_bf16 v[92:95], v[146:149], v[202:205], v[92:95]
	v_mfma_f32_16x16x32_bf16 v[88:91], v[160:163], v[202:205], v[88:91]
	v_mfma_f32_16x16x32_bf16 v[76:79], v[146:149], v[210:213], v[76:79]
	v_mfma_f32_16x16x32_bf16 v[72:75], v[160:163], v[210:213], v[72:75]
	v_mfma_f32_16x16x32_bf16 v[124:127], v[156:159], v[190:193], v[124:127]
	v_mfma_f32_16x16x32_bf16 v[120:123], v[164:167], v[190:193], v[120:123]
	v_mfma_f32_16x16x32_bf16 v[108:111], v[156:159], v[198:201], v[108:111]
	v_mfma_f32_16x16x32_bf16 v[104:107], v[164:167], v[198:201], v[104:107]
	v_mfma_f32_16x16x32_bf16 v[92:95], v[156:159], v[206:209], v[92:95]
	v_mfma_f32_16x16x32_bf16 v[88:91], v[164:167], v[206:209], v[88:91]
	v_mfma_f32_16x16x32_bf16 v[76:79], v[156:159], v[214:217], v[76:79]
	v_mfma_f32_16x16x32_bf16 v[72:75], v[164:167], v[214:217], v[72:75]
	s_setprio 0
	s_setprio 1
	v_mfma_f32_16x16x32_bf16 v[116:119], v[168:171], v[186:189], v[116:119]
	v_mfma_f32_16x16x32_bf16 v[112:115], v[176:179], v[186:189], v[112:115]
	v_mfma_f32_16x16x32_bf16 v[100:103], v[168:171], v[194:197], v[100:103]
	v_mfma_f32_16x16x32_bf16 v[96:99], v[176:179], v[194:197], v[96:99]
	v_mfma_f32_16x16x32_bf16 v[84:87], v[168:171], v[202:205], v[84:87]
	v_mfma_f32_16x16x32_bf16 v[80:83], v[176:179], v[202:205], v[80:83]
	v_mfma_f32_16x16x32_bf16 v[68:71], v[168:171], v[210:213], v[68:71]
	v_mfma_f32_16x16x32_bf16 v[64:67], v[176:179], v[210:213], v[64:67]
	v_mfma_f32_16x16x32_bf16 v[116:119], v[172:175], v[190:193], v[116:119]
	v_mfma_f32_16x16x32_bf16 v[112:115], v[180:183], v[190:193], v[112:115]
	v_mfma_f32_16x16x32_bf16 v[100:103], v[172:175], v[198:201], v[100:103]
	v_mfma_f32_16x16x32_bf16 v[96:99], v[180:183], v[198:201], v[96:99]
	v_mfma_f32_16x16x32_bf16 v[84:87], v[172:175], v[206:209], v[84:87]
	v_mfma_f32_16x16x32_bf16 v[80:83], v[180:183], v[206:209], v[80:83]
	v_mfma_f32_16x16x32_bf16 v[68:71], v[172:175], v[214:217], v[68:71]
	v_mfma_f32_16x16x32_bf16 v[64:67], v[180:183], v[214:217], v[64:67]
	s_setprio 0
	s_barrier
	s_add_i32 s65, s50, s31
	v_lshl_add_u64 v[224:225], s[66:67], 0, v[130:131]
	s_mov_b32 m0, s65
	ds_read_b128 v[186:189], v155 offset:16384
	ds_read_b128 v[190:193], v155 offset:17408
	ds_read_b128 v[194:197], v155 offset:18432
	ds_read_b128 v[198:201], v155 offset:19456
	ds_read_b128 v[202:205], v155 offset:20480
	ds_read_b128 v[206:209], v155 offset:21504
	ds_read_b128 v[210:213], v155 offset:22528
	ds_read_b128 v[214:217], v155 offset:23552
	global_load_lds_dwordx4 v[224:225], off
	s_add_i32 m0, s65, 0x2000
	v_lshl_add_u64 v[226:227], s[66:67], 0, v[134:135]
	s_add_u32 s66, s66, s18
	s_addc_u32 s67, s67, s19
	s_add_i32 s65, s51, s31
	global_load_lds_dwordx4 v[226:227], off
	v_lshl_add_u64 v[228:229], s[66:67], 0, v[130:131]
	s_mov_b32 m0, s65
	v_lshl_add_u64 v[230:231], s[66:67], 0, v[134:135]
	global_load_lds_dwordx4 v[228:229], off
	s_add_i32 m0, s65, 0x2000
	v_lshl_add_u64 v[232:233], s[58:59], 0, v[128:129]
	global_load_lds_dwordx4 v[230:231], off
	v_lshl_add_u64 v[234:235], s[58:59], 0, v[132:133]
	s_waitcnt vmcnt(6)
	s_waitcnt lgkmcnt(0)
	s_barrier
	s_setprio 1
	s_waitcnt lgkmcnt(0)
	v_mfma_f32_16x16x32_bf16 v[60:63], v[146:149], v[186:189], v[60:63]
	v_mfma_f32_16x16x32_bf16 v[56:59], v[160:163], v[186:189], v[56:59]
	v_mfma_f32_16x16x32_bf16 v[44:47], v[146:149], v[194:197], v[44:47]
	v_mfma_f32_16x16x32_bf16 v[40:43], v[160:163], v[194:197], v[40:43]
	v_mfma_f32_16x16x32_bf16 v[28:31], v[146:149], v[202:205], v[28:31]
	v_mfma_f32_16x16x32_bf16 v[24:27], v[160:163], v[202:205], v[24:27]
	v_mfma_f32_16x16x32_bf16 v[12:15], v[146:149], v[210:213], v[12:15]
	v_mfma_f32_16x16x32_bf16 v[8:11], v[160:163], v[210:213], v[8:11]
	v_mfma_f32_16x16x32_bf16 v[60:63], v[156:159], v[190:193], v[60:63]
	v_mfma_f32_16x16x32_bf16 v[56:59], v[164:167], v[190:193], v[56:59]
	v_mfma_f32_16x16x32_bf16 v[44:47], v[156:159], v[198:201], v[44:47]
	v_mfma_f32_16x16x32_bf16 v[40:43], v[164:167], v[198:201], v[40:43]
	v_mfma_f32_16x16x32_bf16 v[28:31], v[156:159], v[206:209], v[28:31]
	v_mfma_f32_16x16x32_bf16 v[24:27], v[164:167], v[206:209], v[24:27]
	v_mfma_f32_16x16x32_bf16 v[12:15], v[156:159], v[214:217], v[12:15]
	v_mfma_f32_16x16x32_bf16 v[8:11], v[164:167], v[214:217], v[8:11]
	s_setprio 0
	s_setprio 1
	v_mfma_f32_16x16x32_bf16 v[52:55], v[168:171], v[186:189], v[52:55]
	v_mfma_f32_16x16x32_bf16 v[48:51], v[176:179], v[186:189], v[48:51]
	v_mfma_f32_16x16x32_bf16 v[36:39], v[168:171], v[194:197], v[36:39]
	v_mfma_f32_16x16x32_bf16 v[32:35], v[176:179], v[194:197], v[32:35]
	v_mfma_f32_16x16x32_bf16 v[20:23], v[168:171], v[202:205], v[20:23]
	v_mfma_f32_16x16x32_bf16 v[16:19], v[176:179], v[202:205], v[16:19]
	v_mfma_f32_16x16x32_bf16 v[4:7], v[168:171], v[210:213], v[4:7]
	v_mfma_f32_16x16x32_bf16 v[0:3], v[176:179], v[210:213], v[0:3]
	v_mfma_f32_16x16x32_bf16 v[52:55], v[172:175], v[190:193], v[52:55]
	v_mfma_f32_16x16x32_bf16 v[48:51], v[180:183], v[190:193], v[48:51]
	v_mfma_f32_16x16x32_bf16 v[36:39], v[172:175], v[198:201], v[36:39]
	v_mfma_f32_16x16x32_bf16 v[32:35], v[180:183], v[198:201], v[32:35]
	v_mfma_f32_16x16x32_bf16 v[20:23], v[172:175], v[206:209], v[20:23]
	v_mfma_f32_16x16x32_bf16 v[16:19], v[180:183], v[206:209], v[16:19]
	v_mfma_f32_16x16x32_bf16 v[4:7], v[172:175], v[214:217], v[4:7]
	v_mfma_f32_16x16x32_bf16 v[0:3], v[180:183], v[214:217], v[0:3]
	s_setprio 0
	s_barrier
	s_add_i32 s65, 0, 0x18000
	v_add_u32_e32 v136, s65, v151
	s_add_i32 s66, 0, 0x1c000
	ds_read_b128 v[146:149], v136
	ds_read_b128 v[156:159], v136 offset:1024
	ds_read_b128 v[160:163], v136 offset:2048
	ds_read_b128 v[164:167], v136 offset:3072
	v_add_u32_e32 v136, s66, v151
	ds_read_b128 v[168:171], v136
	ds_read_b128 v[172:175], v136 offset:1024
	ds_read_b128 v[176:179], v136 offset:2048
	ds_read_b128 v[180:183], v136 offset:3072
	s_add_u32 s58, s58, s18
	s_addc_u32 s59, s59, s19
	s_mov_b32 m0, s3
	s_nop 0
	global_load_lds_dwordx4 v[232:233], off
	s_mov_b32 m0, s28
	s_nop 0
	global_load_lds_dwordx4 v[234:235], off
	s_mov_b32 m0, s33
	v_lshl_add_u64 v[236:237], s[58:59], 0, v[128:129]
	ds_read_b128 v[186:189], v155 offset:32768
	ds_read_b128 v[190:193], v155 offset:33792
	ds_read_b128 v[194:197], v155 offset:34816
	ds_read_b128 v[198:201], v155 offset:35840
	ds_read_b128 v[202:205], v155 offset:36864
	ds_read_b128 v[206:209], v155 offset:37888
	ds_read_b128 v[210:213], v155 offset:38912
	ds_read_b128 v[214:217], v155 offset:39936
	global_load_lds_dwordx4 v[236:237], off
	v_lshl_add_u64 v[236:237], s[58:59], 0, v[132:133]
	s_mov_b32 m0, s44
	s_nop 0
	global_load_lds_dwordx4 v[236:237], off
	s_waitcnt vmcnt(8)
	s_waitcnt lgkmcnt(0)
	s_barrier
	s_setprio 1
	s_waitcnt lgkmcnt(0)
	v_mfma_f32_16x16x32_bf16 v[124:127], v[146:149], v[186:189], v[124:127]
	v_mfma_f32_16x16x32_bf16 v[120:123], v[160:163], v[186:189], v[120:123]
	v_mfma_f32_16x16x32_bf16 v[108:111], v[146:149], v[194:197], v[108:111]
	v_mfma_f32_16x16x32_bf16 v[104:107], v[160:163], v[194:197], v[104:107]
	v_mfma_f32_16x16x32_bf16 v[92:95], v[146:149], v[202:205], v[92:95]
	v_mfma_f32_16x16x32_bf16 v[88:91], v[160:163], v[202:205], v[88:91]
	v_mfma_f32_16x16x32_bf16 v[76:79], v[146:149], v[210:213], v[76:79]
	v_mfma_f32_16x16x32_bf16 v[72:75], v[160:163], v[210:213], v[72:75]
	v_mfma_f32_16x16x32_bf16 v[124:127], v[156:159], v[190:193], v[124:127]
	v_mfma_f32_16x16x32_bf16 v[120:123], v[164:167], v[190:193], v[120:123]
	v_mfma_f32_16x16x32_bf16 v[108:111], v[156:159], v[198:201], v[108:111]
	v_mfma_f32_16x16x32_bf16 v[104:107], v[164:167], v[198:201], v[104:107]
	v_mfma_f32_16x16x32_bf16 v[92:95], v[156:159], v[206:209], v[92:95]
	v_mfma_f32_16x16x32_bf16 v[88:91], v[164:167], v[206:209], v[88:91]
	v_mfma_f32_16x16x32_bf16 v[76:79], v[156:159], v[214:217], v[76:79]
	v_mfma_f32_16x16x32_bf16 v[72:75], v[164:167], v[214:217], v[72:75]
	s_setprio 0
	s_setprio 1
	v_mfma_f32_16x16x32_bf16 v[116:119], v[168:171], v[186:189], v[116:119]
	v_mfma_f32_16x16x32_bf16 v[112:115], v[176:179], v[186:189], v[112:115]
	v_mfma_f32_16x16x32_bf16 v[100:103], v[168:171], v[194:197], v[100:103]
	v_mfma_f32_16x16x32_bf16 v[96:99], v[176:179], v[194:197], v[96:99]
	v_mfma_f32_16x16x32_bf16 v[84:87], v[168:171], v[202:205], v[84:87]
	v_mfma_f32_16x16x32_bf16 v[80:83], v[176:179], v[202:205], v[80:83]
	v_mfma_f32_16x16x32_bf16 v[68:71], v[168:171], v[210:213], v[68:71]
	v_mfma_f32_16x16x32_bf16 v[64:67], v[176:179], v[210:213], v[64:67]
	v_mfma_f32_16x16x32_bf16 v[116:119], v[172:175], v[190:193], v[116:119]
	v_mfma_f32_16x16x32_bf16 v[112:115], v[180:183], v[190:193], v[112:115]
	v_mfma_f32_16x16x32_bf16 v[100:103], v[172:175], v[198:201], v[100:103]
	v_mfma_f32_16x16x32_bf16 v[96:99], v[180:183], v[198:201], v[96:99]
	v_mfma_f32_16x16x32_bf16 v[84:87], v[172:175], v[206:209], v[84:87]
	v_mfma_f32_16x16x32_bf16 v[80:83], v[180:183], v[206:209], v[80:83]
	v_mfma_f32_16x16x32_bf16 v[68:71], v[172:175], v[214:217], v[68:71]
	v_mfma_f32_16x16x32_bf16 v[64:67], v[180:183], v[214:217], v[64:67]
	s_setprio 0
	s_barrier
	s_add_i32 s58, s65, s31
	v_lshl_add_u64 v[224:225], v[224:225], 0, s[40:41]
	s_mov_b32 m0, s58
	ds_read_b128 v[186:189], v155 offset:49152
	ds_read_b128 v[190:193], v155 offset:50176
	ds_read_b128 v[194:197], v155 offset:51200
	ds_read_b128 v[198:201], v155 offset:52224
	ds_read_b128 v[202:205], v155 offset:53248
	ds_read_b128 v[206:209], v155 offset:54272
	ds_read_b128 v[210:213], v155 offset:55296
	ds_read_b128 v[214:217], v155 offset:56320
	global_load_lds_dwordx4 v[224:225], off
	v_lshl_add_u64 v[224:225], v[226:227], 0, s[40:41]
	s_add_i32 m0, s58, 0x2000
	s_add_i32 s58, s66, s31
	global_load_lds_dwordx4 v[224:225], off
	v_lshl_add_u64 v[224:225], v[228:229], 0, s[40:41]
	s_mov_b32 m0, s58
	s_nop 0
	global_load_lds_dwordx4 v[224:225], off
	v_lshl_add_u64 v[224:225], v[230:231], 0, s[40:41]
	s_add_i32 m0, s58, 0x2000
	s_nop 0
	global_load_lds_dwordx4 v[224:225], off
	s_waitcnt vmcnt(6)
	s_waitcnt lgkmcnt(0)
	s_barrier
	s_setprio 1
	s_waitcnt lgkmcnt(0)
	v_mfma_f32_16x16x32_bf16 v[60:63], v[146:149], v[186:189], v[60:63]
	v_mfma_f32_16x16x32_bf16 v[56:59], v[160:163], v[186:189], v[56:59]
	v_mfma_f32_16x16x32_bf16 v[44:47], v[146:149], v[194:197], v[44:47]
	v_mfma_f32_16x16x32_bf16 v[40:43], v[160:163], v[194:197], v[40:43]
	v_mfma_f32_16x16x32_bf16 v[28:31], v[146:149], v[202:205], v[28:31]
	v_mfma_f32_16x16x32_bf16 v[24:27], v[160:163], v[202:205], v[24:27]
	v_mfma_f32_16x16x32_bf16 v[12:15], v[146:149], v[210:213], v[12:15]
	v_mfma_f32_16x16x32_bf16 v[8:11], v[160:163], v[210:213], v[8:11]
	v_mfma_f32_16x16x32_bf16 v[60:63], v[156:159], v[190:193], v[60:63]
	v_mfma_f32_16x16x32_bf16 v[56:59], v[164:167], v[190:193], v[56:59]
	v_mfma_f32_16x16x32_bf16 v[44:47], v[156:159], v[198:201], v[44:47]
	v_mfma_f32_16x16x32_bf16 v[40:43], v[164:167], v[198:201], v[40:43]
	v_mfma_f32_16x16x32_bf16 v[28:31], v[156:159], v[206:209], v[28:31]
	v_mfma_f32_16x16x32_bf16 v[24:27], v[164:167], v[206:209], v[24:27]
	v_mfma_f32_16x16x32_bf16 v[12:15], v[156:159], v[214:217], v[12:15]
	v_mfma_f32_16x16x32_bf16 v[8:11], v[164:167], v[214:217], v[8:11]
	s_setprio 0
	s_setprio 1
	v_mfma_f32_16x16x32_bf16 v[52:55], v[168:171], v[186:189], v[52:55]
	v_mfma_f32_16x16x32_bf16 v[48:51], v[176:179], v[186:189], v[48:51]
	v_mfma_f32_16x16x32_bf16 v[36:39], v[168:171], v[194:197], v[36:39]
	v_mfma_f32_16x16x32_bf16 v[32:35], v[176:179], v[194:197], v[32:35]
	v_mfma_f32_16x16x32_bf16 v[20:23], v[168:171], v[202:205], v[20:23]
	v_mfma_f32_16x16x32_bf16 v[16:19], v[176:179], v[202:205], v[16:19]
	v_mfma_f32_16x16x32_bf16 v[4:7], v[168:171], v[210:213], v[4:7]
	v_mfma_f32_16x16x32_bf16 v[0:3], v[176:179], v[210:213], v[0:3]
	v_mfma_f32_16x16x32_bf16 v[52:55], v[172:175], v[190:193], v[52:55]
	v_mfma_f32_16x16x32_bf16 v[48:51], v[180:183], v[190:193], v[48:51]
	v_mfma_f32_16x16x32_bf16 v[36:39], v[172:175], v[198:201], v[36:39]
	v_mfma_f32_16x16x32_bf16 v[32:35], v[180:183], v[198:201], v[32:35]
	v_mfma_f32_16x16x32_bf16 v[20:23], v[172:175], v[206:209], v[20:23]
	v_mfma_f32_16x16x32_bf16 v[16:19], v[180:183], v[206:209], v[16:19]
	v_mfma_f32_16x16x32_bf16 v[4:7], v[172:175], v[214:217], v[4:7]
	v_mfma_f32_16x16x32_bf16 v[0:3], v[180:183], v[214:217], v[0:3]
	s_setprio 0
	s_barrier
	s_add_u32 s56, s56, 0x100
	s_addc_u32 s57, s57, 0
	s_add_u32 s62, s62, 0x100
	s_addc_u32 s63, s63, 0
	s_cmp_ge_i32 s64, s45
	s_mov_b32 s58, s64
	s_cbranch_scc0 .LBB0_642
	s_branch .LBB0_643

.LBB0_668:
	s_lshr_b32 s5, s5, 26
	s_add_i32 s5, s4, s5
	v_and_b32_e32 v19, 15, v18
	s_ashr_i32 s49, s5, 6
	v_readlane_b32 s5, v248, 17
	s_sext_i32_i8 s68, s40
	v_and_b32_e32 v23, 48, v18
	v_or_b32_e32 v144, s5, v19
	v_lshlrev_b32_e32 v22, 6, v144
	s_movk_i32 s5, 0x3c0
	s_and_b64 s[6:7], s[6:7], exec
	s_mov_b64 s[40:41], 0x80
	v_and_or_b32 v22, v22, s5, v23
	s_cselect_b32 s5, s62, 0
	v_lshl_add_u64 v[0:1], v[0:1], 0, s[40:41]
	s_add_i32 m0, s45, 0x18000
	s_waitcnt vmcnt(2)
	s_barrier
	global_load_lds_dwordx4 v[0:1], off
	v_lshl_add_u64 v[0:1], v[2:3], 0, s[40:41]
	s_add_i32 m0, s45, 0x1a000
	s_add_i32 s53, s45, 0x8000
	global_load_lds_dwordx4 v[0:1], off
	v_mov_b32_e32 v230, v8
	v_mov_b32_e32 v231, v9
	v_mov_b32_e32 v232, v10
	v_mov_b32_e32 v233, v11
	v_lshl_add_u64 v[0:1], v[8:9], 0, s[40:41]
	s_mov_b32 m0, s53
	s_add_i32 s64, s45, 0xa000
	global_load_lds_dwordx4 v[0:1], off
	v_lshl_add_u64 v[0:1], v[10:11], 0, s[40:41]
	s_mov_b32 m0, s64
	s_sub_i32 s50, s84, s5
	global_load_lds_dwordx4 v[0:1], off
	v_lshl_add_u64 v[0:1], v[4:5], 0, s[40:41]
	s_add_i32 m0, s45, 0x1c000
	v_ashrrev_i32_e32 v20, 1, v18
	global_load_lds_dwordx4 v[0:1], off
	v_lshl_add_u64 v[0:1], v[6:7], 0, s[40:41]
	s_add_i32 m0, s45, 0x1e000
	v_ashrrev_i32_e32 v21, 6, v18
	global_load_lds_dwordx4 v[0:1], off
	v_add_u32_e32 v0, v17, v15
	v_lshlrev_b32_e32 v25, 2, v144
	v_lshlrev_b32_e32 v18, 2, v18
	s_ashr_i32 s51, s50, 31
	v_add_lshl_u32 v0, v0, v16, 1
	v_mov_b32_e32 v1, v133
	v_lshl_add_u32 v24, v21, 10, s89
	v_and_b32_e32 v25, 32, v25
	v_lshl_or_b32 v19, v19, 6, v23
	v_add_lshl_u32 v21, v21, s91, 10
	v_and_b32_e32 v18, 32, v18
	s_waitcnt vmcnt(6)
	s_cmp_gt_i32 s4, 63
	v_lshl_add_u64 v[136:137], s[36:37], 0, v[0:1]
	v_add_u32_e32 v0, v14, v12
	v_and_b32_e32 v20, -8, v20
	v_bitop3_b32 v22, v22, v24, v25 bitop3:0xde
	v_bitop3_b32 v145, v19, v21, v18 bitop3:0xde
	s_cselect_b64 s[42:43], -1, 0
	v_add_lshl_u32 v0, v0, v13, 1
	s_add_i32 s66, 0, 0x10000
	s_add_i32 s67, 0, 0x14000
	s_add_i32 s65, s49, -2
	v_add_u32_e32 v146, s88, v20
	v_lshl_add_u64 v[138:139], s[36:37], 0, v[0:1]
	v_mov_b64_e32 v[140:141], 0x210
	v_mov_b64_e32 v[142:143], 0x20f
	v_add_u32_e32 v147, s66, v145
	v_add_u32_e32 v148, s67, v145
	v_add_u32_e32 v149, 0, v22
	s_barrier
	s_branch .LBB0_671

.LBB0_677:
	s_andn2_b64 vcc, exec, s[42:43]
	s_cbranch_vccnz .Lzx679
	s_add_u32 s58, s58, 0x80
	s_addc_u32 s59, s59, 0
	s_add_u32 s71, s60, 0x100
	s_addc_u32 s78, s61, 0
	s_mov_b32 s60, 0
	ds_read_b128 v[150:153], v147
	ds_read_b128 v[154:157], v147 offset:1024
	ds_read_b128 v[158:161], v147 offset:2048
	ds_read_b128 v[162:165], v147 offset:3072
	ds_read_b128 v[166:169], v148
	ds_read_b128 v[170:173], v148 offset:1024
	ds_read_b128 v[174:177], v148 offset:2048
	ds_read_b128 v[178:181], v148 offset:3072
	s_add_i32 s79, s60, 2
	s_add_u32 s80, s58, 0x80
	s_addc_u32 s61, s59, 0
	s_cmp_eq_u32 s65, s60
	s_cselect_b32 s60, s4, s80
	s_cselect_b32 s61, s5, s61
	s_cselect_b32 s81, s57, s78
	s_cselect_b32 s80, s56, s71
	v_lshl_add_u64 v[182:183], v[230:231], 0, s[40:41]
	s_mov_b32 m0, s53
	s_nop 0
	global_load_lds_dwordx4 v[182:183], off
	v_lshl_add_u64 v[182:183], v[232:233], 0, s[40:41]
	s_mov_b32 m0, s64
	s_nop 0
	global_load_lds_dwordx4 v[182:183], off
	v_lshl_add_u64 v[182:183], s[58:59], 0, v[136:137]
	s_add_i32 m0, s45, 0xc000
	ds_read_b128 v[186:189], v149
	ds_read_b128 v[190:193], v149 offset:1024
	ds_read_b128 v[194:197], v149 offset:2048
	ds_read_b128 v[198:201], v149 offset:3072
	ds_read_b128 v[202:205], v149 offset:4096
	ds_read_b128 v[206:209], v149 offset:5120
	ds_read_b128 v[210:213], v149 offset:6144
	ds_read_b128 v[214:217], v149 offset:7168
	global_load_lds_dwordx4 v[182:183], off
	v_lshl_add_u64 v[182:183], s[58:59], 0, v[138:139]
	s_add_i32 m0, s45, 0xe000
	s_nop 0
	global_load_lds_dwordx4 v[182:183], off
	s_waitcnt vmcnt(8)
	s_waitcnt lgkmcnt(0)
	s_barrier
	s_setprio 1
	s_waitcnt lgkmcnt(0)
	v_mfma_f32_16x16x32_bf16 v[120:123], v[150:153], v[186:189], 0
	v_mfma_f32_16x16x32_bf16 v[124:127], v[158:161], v[186:189], 0
	v_mfma_f32_16x16x32_bf16 v[108:111], v[150:153], v[194:197], 0
	v_mfma_f32_16x16x32_bf16 v[104:107], v[158:161], v[194:197], 0
	v_mfma_f32_16x16x32_bf16 v[92:95], v[150:153], v[202:205], 0
	v_mfma_f32_16x16x32_bf16 v[88:91], v[158:161], v[202:205], 0
	v_mfma_f32_16x16x32_bf16 v[76:79], v[150:153], v[210:213], 0
	v_mfma_f32_16x16x32_bf16 v[72:75], v[158:161], v[210:213], 0
	v_mfma_f32_16x16x32_bf16 v[120:123], v[154:157], v[190:193], v[120:123]
	v_mfma_f32_16x16x32_bf16 v[124:127], v[162:165], v[190:193], v[124:127]
	v_mfma_f32_16x16x32_bf16 v[108:111], v[154:157], v[198:201], v[108:111]
	v_mfma_f32_16x16x32_bf16 v[104:107], v[162:165], v[198:201], v[104:107]
	v_mfma_f32_16x16x32_bf16 v[92:95], v[154:157], v[206:209], v[92:95]
	v_mfma_f32_16x16x32_bf16 v[88:91], v[162:165], v[206:209], v[88:91]
	v_mfma_f32_16x16x32_bf16 v[76:79], v[154:157], v[214:217], v[76:79]
	v_mfma_f32_16x16x32_bf16 v[72:75], v[162:165], v[214:217], v[72:75]
	s_setprio 0
	s_setprio 1
	v_mfma_f32_16x16x32_bf16 v[116:119], v[166:169], v[186:189], 0
	v_mfma_f32_16x16x32_bf16 v[112:115], v[174:177], v[186:189], 0
	v_mfma_f32_16x16x32_bf16 v[100:103], v[166:169], v[194:197], 0
	v_mfma_f32_16x16x32_bf16 v[96:99], v[174:177], v[194:197], 0
	v_mfma_f32_16x16x32_bf16 v[84:87], v[166:169], v[202:205], 0
	v_mfma_f32_16x16x32_bf16 v[80:83], v[174:177], v[202:205], 0
	v_mfma_f32_16x16x32_bf16 v[68:71], v[166:169], v[210:213], 0
	v_mfma_f32_16x16x32_bf16 v[64:67], v[174:177], v[210:213], 0
	v_mfma_f32_16x16x32_bf16 v[116:119], v[170:173], v[190:193], v[116:119]
	v_mfma_f32_16x16x32_bf16 v[112:115], v[178:181], v[190:193], v[112:115]
	v_mfma_f32_16x16x32_bf16 v[100:103], v[170:173], v[198:201], v[100:103]
	v_mfma_f32_16x16x32_bf16 v[96:99], v[178:181], v[198:201], v[96:99]
	v_mfma_f32_16x16x32_bf16 v[84:87], v[170:173], v[206:209], v[84:87]
	v_mfma_f32_16x16x32_bf16 v[80:83], v[178:181], v[206:209], v[80:83]
	v_mfma_f32_16x16x32_bf16 v[68:71], v[170:173], v[214:217], v[68:71]
	v_mfma_f32_16x16x32_bf16 v[64:67], v[178:181], v[214:217], v[64:67]
	s_setprio 0
	s_barrier
	s_add_i32 s82, s66, s31
	v_lshl_add_u64 v[182:183], s[80:81], 0, v[132:133]
	s_mov_b32 m0, s82
	ds_read_b128 v[186:189], v149 offset:16384
	ds_read_b128 v[190:193], v149 offset:17408
	ds_read_b128 v[194:197], v149 offset:18432
	ds_read_b128 v[198:201], v149 offset:19456
	ds_read_b128 v[202:205], v149 offset:20480
	ds_read_b128 v[206:209], v149 offset:21504
	ds_read_b128 v[210:213], v149 offset:22528
	ds_read_b128 v[214:217], v149 offset:23552
	global_load_lds_dwordx4 v[182:183], off
	s_add_i32 m0, s82, 0x2000
	v_lshl_add_u64 v[224:225], s[80:81], 0, v[128:129]
	s_add_u32 s80, s80, s36
	s_addc_u32 s81, s81, s37
	s_add_i32 s82, s67, s31
	global_load_lds_dwordx4 v[224:225], off
	v_lshl_add_u64 v[226:227], s[80:81], 0, v[132:133]
	s_mov_b32 m0, s82
	v_lshl_add_u64 v[228:229], s[80:81], 0, v[128:129]
	global_load_lds_dwordx4 v[226:227], off
	s_add_i32 m0, s82, 0x2000
	v_lshl_add_u64 v[230:231], s[60:61], 0, v[134:135]
	global_load_lds_dwordx4 v[228:229], off
	v_lshl_add_u64 v[232:233], s[60:61], 0, v[130:131]
	s_waitcnt vmcnt(6)
	s_waitcnt lgkmcnt(0)
	s_barrier
	s_setprio 1
	s_waitcnt lgkmcnt(0)
	v_mfma_f32_16x16x32_bf16 v[60:63], v[150:153], v[186:189], 0
	v_mfma_f32_16x16x32_bf16 v[56:59], v[158:161], v[186:189], 0
	v_mfma_f32_16x16x32_bf16 v[44:47], v[150:153], v[194:197], 0
	v_mfma_f32_16x16x32_bf16 v[40:43], v[158:161], v[194:197], 0
	v_mfma_f32_16x16x32_bf16 v[28:31], v[150:153], v[202:205], 0
	v_mfma_f32_16x16x32_bf16 v[24:27], v[158:161], v[202:205], 0
	v_mfma_f32_16x16x32_bf16 v[12:15], v[150:153], v[210:213], 0
	v_mfma_f32_16x16x32_bf16 v[8:11], v[158:161], v[210:213], 0
	v_mfma_f32_16x16x32_bf16 v[60:63], v[154:157], v[190:193], v[60:63]
	v_mfma_f32_16x16x32_bf16 v[56:59], v[162:165], v[190:193], v[56:59]
	v_mfma_f32_16x16x32_bf16 v[44:47], v[154:157], v[198:201], v[44:47]
	v_mfma_f32_16x16x32_bf16 v[40:43], v[162:165], v[198:201], v[40:43]
	v_mfma_f32_16x16x32_bf16 v[28:31], v[154:157], v[206:209], v[28:31]
	v_mfma_f32_16x16x32_bf16 v[24:27], v[162:165], v[206:209], v[24:27]
	v_mfma_f32_16x16x32_bf16 v[12:15], v[154:157], v[214:217], v[12:15]
	v_mfma_f32_16x16x32_bf16 v[8:11], v[162:165], v[214:217], v[8:11]
	s_setprio 0
	s_setprio 1
	v_mfma_f32_16x16x32_bf16 v[52:55], v[166:169], v[186:189], 0
	v_mfma_f32_16x16x32_bf16 v[48:51], v[174:177], v[186:189], 0
	v_mfma_f32_16x16x32_bf16 v[36:39], v[166:169], v[194:197], 0
	v_mfma_f32_16x16x32_bf16 v[32:35], v[174:177], v[194:197], 0
	v_mfma_f32_16x16x32_bf16 v[20:23], v[166:169], v[202:205], 0
	v_mfma_f32_16x16x32_bf16 v[16:19], v[174:177], v[202:205], 0
	v_mfma_f32_16x16x32_bf16 v[4:7], v[166:169], v[210:213], 0
	v_mfma_f32_16x16x32_bf16 v[0:3], v[174:177], v[210:213], 0
	v_mfma_f32_16x16x32_bf16 v[52:55], v[170:173], v[190:193], v[52:55]
	v_mfma_f32_16x16x32_bf16 v[48:51], v[178:181], v[190:193], v[48:51]
	v_mfma_f32_16x16x32_bf16 v[36:39], v[170:173], v[198:201], v[36:39]
	v_mfma_f32_16x16x32_bf16 v[32:35], v[178:181], v[198:201], v[32:35]
	v_mfma_f32_16x16x32_bf16 v[20:23], v[170:173], v[206:209], v[20:23]
	v_mfma_f32_16x16x32_bf16 v[16:19], v[178:181], v[206:209], v[16:19]
	v_mfma_f32_16x16x32_bf16 v[4:7], v[170:173], v[214:217], v[4:7]
	v_mfma_f32_16x16x32_bf16 v[0:3], v[178:181], v[214:217], v[0:3]
	s_setprio 0
	s_barrier
	s_add_i32 s80, 0, 0x18000
	s_add_i32 s81, 0, 0x1c000
	v_add_u32_e32 v162, s80, v145
	v_add_u32_e32 v178, s81, v145
	ds_read_b128 v[150:153], v162
	ds_read_b128 v[154:157], v162 offset:1024
	ds_read_b128 v[158:161], v162 offset:2048
	ds_read_b128 v[162:165], v162 offset:3072
	ds_read_b128 v[166:169], v178
	ds_read_b128 v[170:173], v178 offset:1024
	ds_read_b128 v[174:177], v178 offset:2048
	ds_read_b128 v[178:181], v178 offset:3072
	s_add_u32 s60, s60, s36
	s_addc_u32 s61, s61, s37
	s_mov_b32 m0, s45
	s_nop 0
	global_load_lds_dwordx4 v[230:231], off
	s_mov_b32 m0, s46
	s_nop 0
	global_load_lds_dwordx4 v[232:233], off
	s_mov_b32 m0, s47
	v_lshl_add_u64 v[234:235], s[60:61], 0, v[134:135]
	ds_read_b128 v[186:189], v149 offset:32768
	ds_read_b128 v[190:193], v149 offset:33792
	ds_read_b128 v[194:197], v149 offset:34816
	ds_read_b128 v[198:201], v149 offset:35840
	ds_read_b128 v[202:205], v149 offset:36864
	ds_read_b128 v[206:209], v149 offset:37888
	ds_read_b128 v[210:213], v149 offset:38912
	ds_read_b128 v[214:217], v149 offset:39936
	global_load_lds_dwordx4 v[234:235], off
	v_lshl_add_u64 v[234:235], s[60:61], 0, v[130:131]
	s_mov_b32 m0, s48
	s_nop 0
	global_load_lds_dwordx4 v[234:235], off
	s_waitcnt vmcnt(8)
	s_waitcnt lgkmcnt(0)
	s_barrier
	s_setprio 1
	s_waitcnt lgkmcnt(0)
	v_mfma_f32_16x16x32_bf16 v[120:123], v[150:153], v[186:189], v[120:123]
	v_mfma_f32_16x16x32_bf16 v[124:127], v[158:161], v[186:189], v[124:127]
	v_mfma_f32_16x16x32_bf16 v[108:111], v[150:153], v[194:197], v[108:111]
	v_mfma_f32_16x16x32_bf16 v[104:107], v[158:161], v[194:197], v[104:107]
	v_mfma_f32_16x16x32_bf16 v[92:95], v[150:153], v[202:205], v[92:95]
	v_mfma_f32_16x16x32_bf16 v[88:91], v[158:161], v[202:205], v[88:91]
	v_mfma_f32_16x16x32_bf16 v[76:79], v[150:153], v[210:213], v[76:79]
	v_mfma_f32_16x16x32_bf16 v[72:75], v[158:161], v[210:213], v[72:75]
	v_mfma_f32_16x16x32_bf16 v[120:123], v[154:157], v[190:193], v[120:123]
	v_mfma_f32_16x16x32_bf16 v[124:127], v[162:165], v[190:193], v[124:127]
	v_mfma_f32_16x16x32_bf16 v[108:111], v[154:157], v[198:201], v[108:111]
	v_mfma_f32_16x16x32_bf16 v[104:107], v[162:165], v[198:201], v[104:107]
	v_mfma_f32_16x16x32_bf16 v[92:95], v[154:157], v[206:209], v[92:95]
	v_mfma_f32_16x16x32_bf16 v[88:91], v[162:165], v[206:209], v[88:91]
	v_mfma_f32_16x16x32_bf16 v[76:79], v[154:157], v[214:217], v[76:79]
	v_mfma_f32_16x16x32_bf16 v[72:75], v[162:165], v[214:217], v[72:75]
	s_setprio 0
	s_setprio 1
	v_mfma_f32_16x16x32_bf16 v[116:119], v[166:169], v[186:189], v[116:119]
	v_mfma_f32_16x16x32_bf16 v[112:115], v[174:177], v[186:189], v[112:115]
	v_mfma_f32_16x16x32_bf16 v[100:103], v[166:169], v[194:197], v[100:103]
	v_mfma_f32_16x16x32_bf16 v[96:99], v[174:177], v[194:197], v[96:99]
	v_mfma_f32_16x16x32_bf16 v[84:87], v[166:169], v[202:205], v[84:87]
	v_mfma_f32_16x16x32_bf16 v[80:83], v[174:177], v[202:205], v[80:83]
	v_mfma_f32_16x16x32_bf16 v[68:71], v[166:169], v[210:213], v[68:71]
	v_mfma_f32_16x16x32_bf16 v[64:67], v[174:177], v[210:213], v[64:67]
	v_mfma_f32_16x16x32_bf16 v[116:119], v[170:173], v[190:193], v[116:119]
	v_mfma_f32_16x16x32_bf16 v[112:115], v[178:181], v[190:193], v[112:115]
	v_mfma_f32_16x16x32_bf16 v[100:103], v[170:173], v[198:201], v[100:103]
	v_mfma_f32_16x16x32_bf16 v[96:99], v[178:181], v[198:201], v[96:99]
	v_mfma_f32_16x16x32_bf16 v[84:87], v[170:173], v[206:209], v[84:87]
	v_mfma_f32_16x16x32_bf16 v[80:83], v[178:181], v[206:209], v[80:83]
	v_mfma_f32_16x16x32_bf16 v[68:71], v[170:173], v[214:217], v[68:71]
	v_mfma_f32_16x16x32_bf16 v[64:67], v[178:181], v[214:217], v[64:67]
	s_setprio 0
	s_barrier
	s_add_i32 s60, s80, s31
	v_lshl_add_u64 v[182:183], v[182:183], 0, s[40:41]
	s_mov_b32 m0, s60
	ds_read_b128 v[186:189], v149 offset:49152
	ds_read_b128 v[190:193], v149 offset:50176
	ds_read_b128 v[194:197], v149 offset:51200
	ds_read_b128 v[198:201], v149 offset:52224
	ds_read_b128 v[202:205], v149 offset:53248
	ds_read_b128 v[206:209], v149 offset:54272
	ds_read_b128 v[210:213], v149 offset:55296
	ds_read_b128 v[214:217], v149 offset:56320
	global_load_lds_dwordx4 v[182:183], off
	v_lshl_add_u64 v[182:183], v[224:225], 0, s[40:41]
	s_add_i32 m0, s60, 0x2000
	s_add_i32 s60, s81, s31
	global_load_lds_dwordx4 v[182:183], off
	v_lshl_add_u64 v[182:183], v[226:227], 0, s[40:41]
	s_mov_b32 m0, s60
	s_nop 0
	global_load_lds_dwordx4 v[182:183], off
	v_lshl_add_u64 v[182:183], v[228:229], 0, s[40:41]
	s_add_i32 m0, s60, 0x2000
	s_nop 0
	global_load_lds_dwordx4 v[182:183], off
	s_waitcnt vmcnt(6)
	s_waitcnt lgkmcnt(0)
	s_barrier
	s_setprio 1
	s_waitcnt lgkmcnt(0)
	v_mfma_f32_16x16x32_bf16 v[60:63], v[150:153], v[186:189], v[60:63]
	v_mfma_f32_16x16x32_bf16 v[56:59], v[158:161], v[186:189], v[56:59]
	v_mfma_f32_16x16x32_bf16 v[44:47], v[150:153], v[194:197], v[44:47]
	v_mfma_f32_16x16x32_bf16 v[40:43], v[158:161], v[194:197], v[40:43]
	v_mfma_f32_16x16x32_bf16 v[28:31], v[150:153], v[202:205], v[28:31]
	v_mfma_f32_16x16x32_bf16 v[24:27], v[158:161], v[202:205], v[24:27]
	v_mfma_f32_16x16x32_bf16 v[12:15], v[150:153], v[210:213], v[12:15]
	v_mfma_f32_16x16x32_bf16 v[8:11], v[158:161], v[210:213], v[8:11]
	v_mfma_f32_16x16x32_bf16 v[60:63], v[154:157], v[190:193], v[60:63]
	v_mfma_f32_16x16x32_bf16 v[56:59], v[162:165], v[190:193], v[56:59]
	v_mfma_f32_16x16x32_bf16 v[44:47], v[154:157], v[198:201], v[44:47]
	v_mfma_f32_16x16x32_bf16 v[40:43], v[162:165], v[198:201], v[40:43]
	v_mfma_f32_16x16x32_bf16 v[28:31], v[154:157], v[206:209], v[28:31]
	v_mfma_f32_16x16x32_bf16 v[24:27], v[162:165], v[206:209], v[24:27]
	v_mfma_f32_16x16x32_bf16 v[12:15], v[154:157], v[214:217], v[12:15]
	v_mfma_f32_16x16x32_bf16 v[8:11], v[162:165], v[214:217], v[8:11]
	s_setprio 0
	s_setprio 1
	v_mfma_f32_16x16x32_bf16 v[52:55], v[166:169], v[186:189], v[52:55]
	v_mfma_f32_16x16x32_bf16 v[48:51], v[174:177], v[186:189], v[48:51]
	v_mfma_f32_16x16x32_bf16 v[36:39], v[166:169], v[194:197], v[36:39]
	v_mfma_f32_16x16x32_bf16 v[32:35], v[174:177], v[194:197], v[32:35]
	v_mfma_f32_16x16x32_bf16 v[20:23], v[166:169], v[202:205], v[20:23]
	v_mfma_f32_16x16x32_bf16 v[16:19], v[174:177], v[202:205], v[16:19]
	v_mfma_f32_16x16x32_bf16 v[4:7], v[166:169], v[210:213], v[4:7]
	v_mfma_f32_16x16x32_bf16 v[0:3], v[174:177], v[210:213], v[0:3]
	v_mfma_f32_16x16x32_bf16 v[52:55], v[170:173], v[190:193], v[52:55]
	v_mfma_f32_16x16x32_bf16 v[48:51], v[178:181], v[190:193], v[48:51]
	v_mfma_f32_16x16x32_bf16 v[36:39], v[170:173], v[198:201], v[36:39]
	v_mfma_f32_16x16x32_bf16 v[32:35], v[178:181], v[198:201], v[32:35]
	v_mfma_f32_16x16x32_bf16 v[20:23], v[170:173], v[206:209], v[20:23]
	v_mfma_f32_16x16x32_bf16 v[16:19], v[178:181], v[206:209], v[16:19]
	v_mfma_f32_16x16x32_bf16 v[4:7], v[170:173], v[214:217], v[4:7]
	v_mfma_f32_16x16x32_bf16 v[0:3], v[178:181], v[214:217], v[0:3]
	s_setprio 0
	s_barrier
	s_add_u32 s58, s58, 0x100
	s_addc_u32 s59, s59, 0
	s_add_u32 s71, s71, 0x100
	s_addc_u32 s78, s78, 0
	s_cmp_ge_i32 s79, s49
	s_mov_b32 s60, s79
	s_cbranch_scc1 .LBB0_681
.LBB0_679:
	ds_read_b128 v[150:153], v147
	ds_read_b128 v[154:157], v147 offset:1024
	ds_read_b128 v[158:161], v147 offset:2048
	ds_read_b128 v[162:165], v147 offset:3072
	ds_read_b128 v[166:169], v148
	ds_read_b128 v[170:173], v148 offset:1024
	ds_read_b128 v[174:177], v148 offset:2048
	ds_read_b128 v[178:181], v148 offset:3072
	s_add_i32 s79, s60, 2
	s_add_u32 s80, s58, 0x80
	s_addc_u32 s61, s59, 0
	s_cmp_eq_u32 s65, s60
	s_cselect_b32 s60, s4, s80
	s_cselect_b32 s61, s5, s61
	s_cselect_b32 s81, s57, s78
	s_cselect_b32 s80, s56, s71
	v_lshl_add_u64 v[182:183], v[230:231], 0, s[40:41]
	s_mov_b32 m0, s53
	s_nop 0
	global_load_lds_dwordx4 v[182:183], off
	v_lshl_add_u64 v[182:183], v[232:233], 0, s[40:41]
	s_mov_b32 m0, s64
	s_nop 0
	global_load_lds_dwordx4 v[182:183], off
	v_lshl_add_u64 v[182:183], s[58:59], 0, v[136:137]
	s_add_i32 m0, s45, 0xc000
	ds_read_b128 v[186:189], v149
	ds_read_b128 v[190:193], v149 offset:1024
	ds_read_b128 v[194:197], v149 offset:2048
	ds_read_b128 v[198:201], v149 offset:3072
	ds_read_b128 v[202:205], v149 offset:4096
	ds_read_b128 v[206:209], v149 offset:5120
	ds_read_b128 v[210:213], v149 offset:6144
	ds_read_b128 v[214:217], v149 offset:7168
	global_load_lds_dwordx4 v[182:183], off
	v_lshl_add_u64 v[182:183], s[58:59], 0, v[138:139]
	s_add_i32 m0, s45, 0xe000
	s_nop 0
	global_load_lds_dwordx4 v[182:183], off
	s_waitcnt vmcnt(8)
	s_waitcnt lgkmcnt(0)
	s_barrier
	s_setprio 1
	s_waitcnt lgkmcnt(0)
	v_mfma_f32_16x16x32_bf16 v[120:123], v[150:153], v[186:189], v[120:123]
	v_mfma_f32_16x16x32_bf16 v[124:127], v[158:161], v[186:189], v[124:127]
	v_mfma_f32_16x16x32_bf16 v[108:111], v[150:153], v[194:197], v[108:111]
	v_mfma_f32_16x16x32_bf16 v[104:107], v[158:161], v[194:197], v[104:107]
	v_mfma_f32_16x16x32_bf16 v[92:95], v[150:153], v[202:205], v[92:95]
	v_mfma_f32_16x16x32_bf16 v[88:91], v[158:161], v[202:205], v[88:91]
	v_mfma_f32_16x16x32_bf16 v[76:79], v[150:153], v[210:213], v[76:79]
	v_mfma_f32_16x16x32_bf16 v[72:75], v[158:161], v[210:213], v[72:75]
	v_mfma_f32_16x16x32_bf16 v[120:123], v[154:157], v[190:193], v[120:123]
	v_mfma_f32_16x16x32_bf16 v[124:127], v[162:165], v[190:193], v[124:127]
	v_mfma_f32_16x16x32_bf16 v[108:111], v[154:157], v[198:201], v[108:111]
	v_mfma_f32_16x16x32_bf16 v[104:107], v[162:165], v[198:201], v[104:107]
	v_mfma_f32_16x16x32_bf16 v[92:95], v[154:157], v[206:209], v[92:95]
	v_mfma_f32_16x16x32_bf16 v[88:91], v[162:165], v[206:209], v[88:91]
	v_mfma_f32_16x16x32_bf16 v[76:79], v[154:157], v[214:217], v[76:79]
	v_mfma_f32_16x16x32_bf16 v[72:75], v[162:165], v[214:217], v[72:75]
	s_setprio 0
	s_setprio 1
	v_mfma_f32_16x16x32_bf16 v[116:119], v[166:169], v[186:189], v[116:119]
	v_mfma_f32_16x16x32_bf16 v[112:115], v[174:177], v[186:189], v[112:115]
	v_mfma_f32_16x16x32_bf16 v[100:103], v[166:169], v[194:197], v[100:103]
	v_mfma_f32_16x16x32_bf16 v[96:99], v[174:177], v[194:197], v[96:99]
	v_mfma_f32_16x16x32_bf16 v[84:87], v[166:169], v[202:205], v[84:87]
	v_mfma_f32_16x16x32_bf16 v[80:83], v[174:177], v[202:205], v[80:83]
	v_mfma_f32_16x16x32_bf16 v[68:71], v[166:169], v[210:213], v[68:71]
	v_mfma_f32_16x16x32_bf16 v[64:67], v[174:177], v[210:213], v[64:67]
	v_mfma_f32_16x16x32_bf16 v[116:119], v[170:173], v[190:193], v[116:119]
	v_mfma_f32_16x16x32_bf16 v[112:115], v[178:181], v[190:193], v[112:115]
	v_mfma_f32_16x16x32_bf16 v[100:103], v[170:173], v[198:201], v[100:103]
	v_mfma_f32_16x16x32_bf16 v[96:99], v[178:181], v[198:201], v[96:99]
	v_mfma_f32_16x16x32_bf16 v[84:87], v[170:173], v[206:209], v[84:87]
	v_mfma_f32_16x16x32_bf16 v[80:83], v[178:181], v[206:209], v[80:83]
	v_mfma_f32_16x16x32_bf16 v[68:71], v[170:173], v[214:217], v[68:71]
	v_mfma_f32_16x16x32_bf16 v[64:67], v[178:181], v[214:217], v[64:67]
	s_setprio 0
	s_barrier
	s_add_i32 s82, s66, s31
	v_lshl_add_u64 v[182:183], s[80:81], 0, v[132:133]
	s_mov_b32 m0, s82
	ds_read_b128 v[186:189], v149 offset:16384
	ds_read_b128 v[190:193], v149 offset:17408
	ds_read_b128 v[194:197], v149 offset:18432
	ds_read_b128 v[198:201], v149 offset:19456
	ds_read_b128 v[202:205], v149 offset:20480
	ds_read_b128 v[206:209], v149 offset:21504
	ds_read_b128 v[210:213], v149 offset:22528
	ds_read_b128 v[214:217], v149 offset:23552
	global_load_lds_dwordx4 v[182:183], off
	s_add_i32 m0, s82, 0x2000
	v_lshl_add_u64 v[224:225], s[80:81], 0, v[128:129]
	s_add_u32 s80, s80, s36
	s_addc_u32 s81, s81, s37
	s_add_i32 s82, s67, s31
	global_load_lds_dwordx4 v[224:225], off
	v_lshl_add_u64 v[226:227], s[80:81], 0, v[132:133]
	s_mov_b32 m0, s82
	v_lshl_add_u64 v[228:229], s[80:81], 0, v[128:129]
	global_load_lds_dwordx4 v[226:227], off
	s_add_i32 m0, s82, 0x2000
	v_lshl_add_u64 v[230:231], s[60:61], 0, v[134:135]
	global_load_lds_dwordx4 v[228:229], off
	v_lshl_add_u64 v[232:233], s[60:61], 0, v[130:131]
	s_waitcnt vmcnt(6)
	s_waitcnt lgkmcnt(0)
	s_barrier
	s_setprio 1
	s_waitcnt lgkmcnt(0)
	v_mfma_f32_16x16x32_bf16 v[60:63], v[150:153], v[186:189], v[60:63]
	v_mfma_f32_16x16x32_bf16 v[56:59], v[158:161], v[186:189], v[56:59]
	v_mfma_f32_16x16x32_bf16 v[44:47], v[150:153], v[194:197], v[44:47]
	v_mfma_f32_16x16x32_bf16 v[40:43], v[158:161], v[194:197], v[40:43]
	v_mfma_f32_16x16x32_bf16 v[28:31], v[150:153], v[202:205], v[28:31]
	v_mfma_f32_16x16x32_bf16 v[24:27], v[158:161], v[202:205], v[24:27]
	v_mfma_f32_16x16x32_bf16 v[12:15], v[150:153], v[210:213], v[12:15]
	v_mfma_f32_16x16x32_bf16 v[8:11], v[158:161], v[210:213], v[8:11]
	v_mfma_f32_16x16x32_bf16 v[60:63], v[154:157], v[190:193], v[60:63]
	v_mfma_f32_16x16x32_bf16 v[56:59], v[162:165], v[190:193], v[56:59]
	v_mfma_f32_16x16x32_bf16 v[44:47], v[154:157], v[198:201], v[44:47]
	v_mfma_f32_16x16x32_bf16 v[40:43], v[162:165], v[198:201], v[40:43]
	v_mfma_f32_16x16x32_bf16 v[28:31], v[154:157], v[206:209], v[28:31]
	v_mfma_f32_16x16x32_bf16 v[24:27], v[162:165], v[206:209], v[24:27]
	v_mfma_f32_16x16x32_bf16 v[12:15], v[154:157], v[214:217], v[12:15]
	v_mfma_f32_16x16x32_bf16 v[8:11], v[162:165], v[214:217], v[8:11]
	s_setprio 0
	s_setprio 1
	v_mfma_f32_16x16x32_bf16 v[52:55], v[166:169], v[186:189], v[52:55]
	v_mfma_f32_16x16x32_bf16 v[48:51], v[174:177], v[186:189], v[48:51]
	v_mfma_f32_16x16x32_bf16 v[36:39], v[166:169], v[194:197], v[36:39]
	v_mfma_f32_16x16x32_bf16 v[32:35], v[174:177], v[194:197], v[32:35]
	v_mfma_f32_16x16x32_bf16 v[20:23], v[166:169], v[202:205], v[20:23]
	v_mfma_f32_16x16x32_bf16 v[16:19], v[174:177], v[202:205], v[16:19]
	v_mfma_f32_16x16x32_bf16 v[4:7], v[166:169], v[210:213], v[4:7]
	v_mfma_f32_16x16x32_bf16 v[0:3], v[174:177], v[210:213], v[0:3]
	v_mfma_f32_16x16x32_bf16 v[52:55], v[170:173], v[190:193], v[52:55]
	v_mfma_f32_16x16x32_bf16 v[48:51], v[178:181], v[190:193], v[48:51]
	v_mfma_f32_16x16x32_bf16 v[36:39], v[170:173], v[198:201], v[36:39]
	v_mfma_f32_16x16x32_bf16 v[32:35], v[178:181], v[198:201], v[32:35]
	v_mfma_f32_16x16x32_bf16 v[20:23], v[170:173], v[206:209], v[20:23]
	v_mfma_f32_16x16x32_bf16 v[16:19], v[178:181], v[206:209], v[16:19]
	v_mfma_f32_16x16x32_bf16 v[4:7], v[170:173], v[214:217], v[4:7]
	v_mfma_f32_16x16x32_bf16 v[0:3], v[178:181], v[214:217], v[0:3]
	s_setprio 0
	s_barrier
	s_add_i32 s80, 0, 0x18000
	s_add_i32 s81, 0, 0x1c000
	v_add_u32_e32 v162, s80, v145
	v_add_u32_e32 v178, s81, v145
	ds_read_b128 v[150:153], v162
	ds_read_b128 v[154:157], v162 offset:1024
	ds_read_b128 v[158:161], v162 offset:2048
	ds_read_b128 v[162:165], v162 offset:3072
	ds_read_b128 v[166:169], v178
	ds_read_b128 v[170:173], v178 offset:1024
	ds_read_b128 v[174:177], v178 offset:2048
	ds_read_b128 v[178:181], v178 offset:3072
	s_add_u32 s60, s60, s36
	s_addc_u32 s61, s61, s37
	s_mov_b32 m0, s45
	s_nop 0
	global_load_lds_dwordx4 v[230:231], off
	s_mov_b32 m0, s46
	s_nop 0
	global_load_lds_dwordx4 v[232:233], off
	s_mov_b32 m0, s47
	v_lshl_add_u64 v[234:235], s[60:61], 0, v[134:135]
	ds_read_b128 v[186:189], v149 offset:32768
	ds_read_b128 v[190:193], v149 offset:33792
	ds_read_b128 v[194:197], v149 offset:34816
	ds_read_b128 v[198:201], v149 offset:35840
	ds_read_b128 v[202:205], v149 offset:36864
	ds_read_b128 v[206:209], v149 offset:37888
	ds_read_b128 v[210:213], v149 offset:38912
	ds_read_b128 v[214:217], v149 offset:39936
	global_load_lds_dwordx4 v[234:235], off
	v_lshl_add_u64 v[234:235], s[60:61], 0, v[130:131]
	s_mov_b32 m0, s48
	s_nop 0
	global_load_lds_dwordx4 v[234:235], off
	s_waitcnt vmcnt(8)
	s_waitcnt lgkmcnt(0)
	s_barrier
	s_setprio 1
	s_waitcnt lgkmcnt(0)
	v_mfma_f32_16x16x32_bf16 v[120:123], v[150:153], v[186:189], v[120:123]
	v_mfma_f32_16x16x32_bf16 v[124:127], v[158:161], v[186:189], v[124:127]
	v_mfma_f32_16x16x32_bf16 v[108:111], v[150:153], v[194:197], v[108:111]
	v_mfma_f32_16x16x32_bf16 v[104:107], v[158:161], v[194:197], v[104:107]
	v_mfma_f32_16x16x32_bf16 v[92:95], v[150:153], v[202:205], v[92:95]
	v_mfma_f32_16x16x32_bf16 v[88:91], v[158:161], v[202:205], v[88:91]
	v_mfma_f32_16x16x32_bf16 v[76:79], v[150:153], v[210:213], v[76:79]
	v_mfma_f32_16x16x32_bf16 v[72:75], v[158:161], v[210:213], v[72:75]
	v_mfma_f32_16x16x32_bf16 v[120:123], v[154:157], v[190:193], v[120:123]
	v_mfma_f32_16x16x32_bf16 v[124:127], v[162:165], v[190:193], v[124:127]
	v_mfma_f32_16x16x32_bf16 v[108:111], v[154:157], v[198:201], v[108:111]
	v_mfma_f32_16x16x32_bf16 v[104:107], v[162:165], v[198:201], v[104:107]
	v_mfma_f32_16x16x32_bf16 v[92:95], v[154:157], v[206:209], v[92:95]
	v_mfma_f32_16x16x32_bf16 v[88:91], v[162:165], v[206:209], v[88:91]
	v_mfma_f32_16x16x32_bf16 v[76:79], v[154:157], v[214:217], v[76:79]
	v_mfma_f32_16x16x32_bf16 v[72:75], v[162:165], v[214:217], v[72:75]
	s_setprio 0
	s_setprio 1
	v_mfma_f32_16x16x32_bf16 v[116:119], v[166:169], v[186:189], v[116:119]
	v_mfma_f32_16x16x32_bf16 v[112:115], v[174:177], v[186:189], v[112:115]
	v_mfma_f32_16x16x32_bf16 v[100:103], v[166:169], v[194:197], v[100:103]
	v_mfma_f32_16x16x32_bf16 v[96:99], v[174:177], v[194:197], v[96:99]
	v_mfma_f32_16x16x32_bf16 v[84:87], v[166:169], v[202:205], v[84:87]
	v_mfma_f32_16x16x32_bf16 v[80:83], v[174:177], v[202:205], v[80:83]
	v_mfma_f32_16x16x32_bf16 v[68:71], v[166:169], v[210:213], v[68:71]
	v_mfma_f32_16x16x32_bf16 v[64:67], v[174:177], v[210:213], v[64:67]
	v_mfma_f32_16x16x32_bf16 v[116:119], v[170:173], v[190:193], v[116:119]
	v_mfma_f32_16x16x32_bf16 v[112:115], v[178:181], v[190:193], v[112:115]
	v_mfma_f32_16x16x32_bf16 v[100:103], v[170:173], v[198:201], v[100:103]
	v_mfma_f32_16x16x32_bf16 v[96:99], v[178:181], v[198:201], v[96:99]
	v_mfma_f32_16x16x32_bf16 v[84:87], v[170:173], v[206:209], v[84:87]
	v_mfma_f32_16x16x32_bf16 v[80:83], v[178:181], v[206:209], v[80:83]
	v_mfma_f32_16x16x32_bf16 v[68:71], v[170:173], v[214:217], v[68:71]
	v_mfma_f32_16x16x32_bf16 v[64:67], v[178:181], v[214:217], v[64:67]
	s_setprio 0
	s_barrier
	s_add_i32 s60, s80, s31
	v_lshl_add_u64 v[182:183], v[182:183], 0, s[40:41]
	s_mov_b32 m0, s60
	ds_read_b128 v[186:189], v149 offset:49152
	ds_read_b128 v[190:193], v149 offset:50176
	ds_read_b128 v[194:197], v149 offset:51200
	ds_read_b128 v[198:201], v149 offset:52224
	ds_read_b128 v[202:205], v149 offset:53248
	ds_read_b128 v[206:209], v149 offset:54272
	ds_read_b128 v[210:213], v149 offset:55296
	ds_read_b128 v[214:217], v149 offset:56320
	global_load_lds_dwordx4 v[182:183], off
	v_lshl_add_u64 v[182:183], v[224:225], 0, s[40:41]
	s_add_i32 m0, s60, 0x2000
	s_add_i32 s60, s81, s31
	global_load_lds_dwordx4 v[182:183], off
	v_lshl_add_u64 v[182:183], v[226:227], 0, s[40:41]
	s_mov_b32 m0, s60
	s_nop 0
	global_load_lds_dwordx4 v[182:183], off
	v_lshl_add_u64 v[182:183], v[228:229], 0, s[40:41]
	s_add_i32 m0, s60, 0x2000
	s_nop 0
	global_load_lds_dwordx4 v[182:183], off
	s_waitcnt vmcnt(6)
	s_waitcnt lgkmcnt(0)
	s_barrier
	s_setprio 1
	s_waitcnt lgkmcnt(0)
	v_mfma_f32_16x16x32_bf16 v[60:63], v[150:153], v[186:189], v[60:63]
	v_mfma_f32_16x16x32_bf16 v[56:59], v[158:161], v[186:189], v[56:59]
	v_mfma_f32_16x16x32_bf16 v[44:47], v[150:153], v[194:197], v[44:47]
	v_mfma_f32_16x16x32_bf16 v[40:43], v[158:161], v[194:197], v[40:43]
	v_mfma_f32_16x16x32_bf16 v[28:31], v[150:153], v[202:205], v[28:31]
	v_mfma_f32_16x16x32_bf16 v[24:27], v[158:161], v[202:205], v[24:27]
	v_mfma_f32_16x16x32_bf16 v[12:15], v[150:153], v[210:213], v[12:15]
	v_mfma_f32_16x16x32_bf16 v[8:11], v[158:161], v[210:213], v[8:11]
	v_mfma_f32_16x16x32_bf16 v[60:63], v[154:157], v[190:193], v[60:63]
	v_mfma_f32_16x16x32_bf16 v[56:59], v[162:165], v[190:193], v[56:59]
	v_mfma_f32_16x16x32_bf16 v[44:47], v[154:157], v[198:201], v[44:47]
	v_mfma_f32_16x16x32_bf16 v[40:43], v[162:165], v[198:201], v[40:43]
	v_mfma_f32_16x16x32_bf16 v[28:31], v[154:157], v[206:209], v[28:31]
	v_mfma_f32_16x16x32_bf16 v[24:27], v[162:165], v[206:209], v[24:27]
	v_mfma_f32_16x16x32_bf16 v[12:15], v[154:157], v[214:217], v[12:15]
	v_mfma_f32_16x16x32_bf16 v[8:11], v[162:165], v[214:217], v[8:11]
	s_setprio 0
	s_setprio 1
	v_mfma_f32_16x16x32_bf16 v[52:55], v[166:169], v[186:189], v[52:55]
	v_mfma_f32_16x16x32_bf16 v[48:51], v[174:177], v[186:189], v[48:51]
	v_mfma_f32_16x16x32_bf16 v[36:39], v[166:169], v[194:197], v[36:39]
	v_mfma_f32_16x16x32_bf16 v[32:35], v[174:177], v[194:197], v[32:35]
	v_mfma_f32_16x16x32_bf16 v[20:23], v[166:169], v[202:205], v[20:23]
	v_mfma_f32_16x16x32_bf16 v[16:19], v[174:177], v[202:205], v[16:19]
	v_mfma_f32_16x16x32_bf16 v[4:7], v[166:169], v[210:213], v[4:7]
	v_mfma_f32_16x16x32_bf16 v[0:3], v[174:177], v[210:213], v[0:3]
	v_mfma_f32_16x16x32_bf16 v[52:55], v[170:173], v[190:193], v[52:55]
	v_mfma_f32_16x16x32_bf16 v[48:51], v[178:181], v[190:193], v[48:51]
	v_mfma_f32_16x16x32_bf16 v[36:39], v[170:173], v[198:201], v[36:39]
	v_mfma_f32_16x16x32_bf16 v[32:35], v[178:181], v[198:201], v[32:35]
	v_mfma_f32_16x16x32_bf16 v[20:23], v[170:173], v[206:209], v[20:23]
	v_mfma_f32_16x16x32_bf16 v[16:19], v[178:181], v[206:209], v[16:19]
	v_mfma_f32_16x16x32_bf16 v[4:7], v[170:173], v[214:217], v[4:7]
	v_mfma_f32_16x16x32_bf16 v[0:3], v[178:181], v[214:217], v[0:3]
	s_setprio 0
	s_barrier
	s_add_u32 s58, s58, 0x100
	s_addc_u32 s59, s59, 0
	s_add_u32 s71, s71, 0x100
	s_addc_u32 s78, s78, 0
	s_cmp_ge_i32 s79, s49
	s_mov_b32 s60, s79
	s_cbranch_scc0 .LBB0_679
	v_readlane_b32 s82, v248, 38
	v_readlane_b32 s83, v248, 39
	s_branch .LBB0_681

.LBB0_1097:
	s_add_u32 s18, s24, 0x1d35000
	s_mov_b64 s[36:37], 0x80
	s_addc_u32 s19, s25, 0
	v_lshl_add_u64 v[8:9], v[8:9], 0, s[36:37]
	s_add_i32 m0, s50, 0x18000
	s_waitcnt vmcnt(2)
	s_barrier
	global_load_lds_dwordx4 v[8:9], off
	v_lshl_add_u64 v[4:5], v[4:5], 0, s[36:37]
	s_add_i32 m0, s50, 0x1a000
	s_add_i32 s57, s50, 0x8000
	global_load_lds_dwordx4 v[4:5], off
	v_mov_b32_e32 v232, v6
	v_mov_b32_e32 v233, v7
	v_mov_b32_e32 v234, v10
	v_mov_b32_e32 v235, v11
	v_lshl_add_u64 v[4:5], v[6:7], 0, s[36:37]
	s_mov_b32 m0, s57
	s_add_i32 s58, s50, 0xa000
	global_load_lds_dwordx4 v[4:5], off
	v_lshl_add_u64 v[4:5], v[10:11], 0, s[36:37]
	s_mov_b32 m0, s58
	v_lshl_add_u64 v[2:3], v[2:3], 0, s[36:37]
	global_load_lds_dwordx4 v[4:5], off
	s_add_i32 m0, s50, 0x1c000
	v_lshl_add_u64 v[0:1], v[0:1], 0, s[36:37]
	global_load_lds_dwordx4 v[2:3], off
	s_add_i32 m0, s50, 0x1e000
	s_lshr_b32 s5, s5, 26
	global_load_lds_dwordx4 v[0:1], off
	s_add_i32 s5, s4, s5
	v_and_b32_e32 v0, 15, v12
	s_ashr_i32 s59, s5, 6
	v_readlane_b32 s5, v248, 17
	v_and_b32_e32 v4, 48, v12
	v_ashrrev_i32_e32 v2, 6, v12
	v_or_b32_e32 v148, s5, v0
	v_lshlrev_b32_e32 v3, 6, v148
	s_movk_i32 s5, 0x3c0
	v_and_or_b32 v3, v3, s5, v4
	v_lshl_or_b32 v0, v0, 6, v4
	v_lshlrev_b32_e32 v4, 2, v12
	v_ashrrev_i32_e32 v1, 1, v12
	v_lshl_add_u32 v5, v2, 10, s89
	v_add_lshl_u32 v2, v2, s91, 10
	v_and_b32_e32 v4, 32, v4
	v_and_b32_e32 v1, -8, v1
	v_bitop3_b32 v149, v0, v2, v4 bitop3:0xde
	v_add_u32_e32 v0, v15, v13
	v_lshlrev_b32_e32 v6, 2, v148
	v_add_u32_e32 v150, s88, v1
	v_add_lshl_u32 v0, v0, v14, 1
	v_mov_b32_e32 v1, v131
	v_and_b32_e32 v6, 32, v6
	s_waitcnt vmcnt(6)
	s_cmp_gt_i32 s4, 63
	v_lshl_add_u64 v[136:137], s[14:15], 0, v[0:1]
	v_add_u32_e32 v0, v18, v16
	v_bitop3_b32 v3, v3, v5, v6 bitop3:0xde
	s_cselect_b64 s[38:39], -1, 0
	v_add_lshl_u32 v0, v0, v17, 1
	s_add_i32 s61, 0, 0x10000
	s_add_i32 s62, 0, 0x14000
	s_brev_b32 s40, 63
	s_add_i32 s60, s59, -2
	v_lshl_add_u64 v[138:139], s[14:15], 0, v[0:1]
	v_mov_b64_e32 v[140:141], 0x200
	v_mov_b64_e32 v[142:143], 0x1ff
	v_add_u32_e32 v151, s61, v149
	v_add_u32_e32 v152, s62, v149
	v_add_u32_e32 v153, 0, v3
	s_mov_b32 s41, -1
	v_mov_b32_e32 v154, 0x358637bd
	s_barrier
	s_branch .LBB0_1100

.LBB0_1110:
	s_andn2_b64 vcc, exec, s[38:39]
	s_cbranch_vccnz .Lzx1112
	s_add_u32 s4, s48, 0x80
	s_addc_u32 s5, s49, 0
	s_add_u32 s33, s46, 0x100
	s_addc_u32 s48, s47, 0
	s_mov_b32 s46, 0
	ds_read_b128 v[144:147], v151
	ds_read_b128 v[156:159], v151 offset:1024
	ds_read_b128 v[160:163], v151 offset:2048
	ds_read_b128 v[164:167], v151 offset:3072
	ds_read_b128 v[168:171], v152
	ds_read_b128 v[172:175], v152 offset:1024
	ds_read_b128 v[176:179], v152 offset:2048
	ds_read_b128 v[180:183], v152 offset:3072
	s_add_i32 s49, s46, 2
	s_add_u32 s52, s4, 0x80
	s_addc_u32 s47, s5, 0
	s_cmp_eq_u32 s60, s46
	s_cselect_b32 s46, s42, s52
	s_cselect_b32 s47, s43, s47
	s_cselect_b32 s53, s45, s48
	s_cselect_b32 s52, s44, s33
	v_lshl_add_u64 v[224:225], v[232:233], 0, s[36:37]
	s_mov_b32 m0, s57
	s_nop 0
	global_load_lds_dwordx4 v[224:225], off
	v_lshl_add_u64 v[224:225], v[234:235], 0, s[36:37]
	s_mov_b32 m0, s58
	s_nop 0
	global_load_lds_dwordx4 v[224:225], off
	v_lshl_add_u64 v[224:225], s[4:5], 0, v[136:137]
	s_add_i32 m0, s50, 0xc000
	ds_read_b128 v[186:189], v153
	ds_read_b128 v[190:193], v153 offset:1024
	ds_read_b128 v[194:197], v153 offset:2048
	ds_read_b128 v[198:201], v153 offset:3072
	ds_read_b128 v[202:205], v153 offset:4096
	ds_read_b128 v[206:209], v153 offset:5120
	ds_read_b128 v[210:213], v153 offset:6144
	ds_read_b128 v[214:217], v153 offset:7168
	global_load_lds_dwordx4 v[224:225], off
	v_lshl_add_u64 v[224:225], s[4:5], 0, v[138:139]
	s_add_i32 m0, s50, 0xe000
	s_nop 0
	global_load_lds_dwordx4 v[224:225], off
	s_waitcnt vmcnt(8)
	s_waitcnt lgkmcnt(0)
	s_barrier
	s_setprio 1
	s_waitcnt lgkmcnt(0)
	v_mfma_f32_16x16x32_bf16 v[124:127], v[144:147], v[186:189], 0
	v_mfma_f32_16x16x32_bf16 v[120:123], v[160:163], v[186:189], 0
	v_mfma_f32_16x16x32_bf16 v[108:111], v[144:147], v[194:197], 0
	v_mfma_f32_16x16x32_bf16 v[104:107], v[160:163], v[194:197], 0
	v_mfma_f32_16x16x32_bf16 v[92:95], v[144:147], v[202:205], 0
	v_mfma_f32_16x16x32_bf16 v[88:91], v[160:163], v[202:205], 0
	v_mfma_f32_16x16x32_bf16 v[76:79], v[144:147], v[210:213], 0
	v_mfma_f32_16x16x32_bf16 v[72:75], v[160:163], v[210:213], 0
	v_mfma_f32_16x16x32_bf16 v[124:127], v[156:159], v[190:193], v[124:127]
	v_mfma_f32_16x16x32_bf16 v[120:123], v[164:167], v[190:193], v[120:123]
	v_mfma_f32_16x16x32_bf16 v[108:111], v[156:159], v[198:201], v[108:111]
	v_mfma_f32_16x16x32_bf16 v[104:107], v[164:167], v[198:201], v[104:107]
	v_mfma_f32_16x16x32_bf16 v[92:95], v[156:159], v[206:209], v[92:95]
	v_mfma_f32_16x16x32_bf16 v[88:91], v[164:167], v[206:209], v[88:91]
	v_mfma_f32_16x16x32_bf16 v[76:79], v[156:159], v[214:217], v[76:79]
	v_mfma_f32_16x16x32_bf16 v[72:75], v[164:167], v[214:217], v[72:75]
	s_setprio 0
	s_setprio 1
	v_mfma_f32_16x16x32_bf16 v[116:119], v[168:171], v[186:189], 0
	v_mfma_f32_16x16x32_bf16 v[112:115], v[176:179], v[186:189], 0
	v_mfma_f32_16x16x32_bf16 v[100:103], v[168:171], v[194:197], 0
	v_mfma_f32_16x16x32_bf16 v[96:99], v[176:179], v[194:197], 0
	v_mfma_f32_16x16x32_bf16 v[84:87], v[168:171], v[202:205], 0
	v_mfma_f32_16x16x32_bf16 v[80:83], v[176:179], v[202:205], 0
	v_mfma_f32_16x16x32_bf16 v[68:71], v[168:171], v[210:213], 0
	v_mfma_f32_16x16x32_bf16 v[64:67], v[176:179], v[210:213], 0
	v_mfma_f32_16x16x32_bf16 v[116:119], v[172:175], v[190:193], v[116:119]
	v_mfma_f32_16x16x32_bf16 v[112:115], v[180:183], v[190:193], v[112:115]
	v_mfma_f32_16x16x32_bf16 v[100:103], v[172:175], v[198:201], v[100:103]
	v_mfma_f32_16x16x32_bf16 v[96:99], v[180:183], v[198:201], v[96:99]
	v_mfma_f32_16x16x32_bf16 v[84:87], v[172:175], v[206:209], v[84:87]
	v_mfma_f32_16x16x32_bf16 v[80:83], v[180:183], v[206:209], v[80:83]
	v_mfma_f32_16x16x32_bf16 v[68:71], v[172:175], v[214:217], v[68:71]
	v_mfma_f32_16x16x32_bf16 v[64:67], v[180:183], v[214:217], v[64:67]
	s_setprio 0
	s_barrier
	s_add_i32 s65, s61, s31
	v_lshl_add_u64 v[224:225], s[52:53], 0, v[130:131]
	s_mov_b32 m0, s65
	ds_read_b128 v[186:189], v153 offset:16384
	ds_read_b128 v[190:193], v153 offset:17408
	ds_read_b128 v[194:197], v153 offset:18432
	ds_read_b128 v[198:201], v153 offset:19456
	ds_read_b128 v[202:205], v153 offset:20480
	ds_read_b128 v[206:209], v153 offset:21504
	ds_read_b128 v[210:213], v153 offset:22528
	ds_read_b128 v[214:217], v153 offset:23552
	global_load_lds_dwordx4 v[224:225], off
	s_add_i32 m0, s65, 0x2000
	v_lshl_add_u64 v[226:227], s[52:53], 0, v[134:135]
	s_add_u32 s52, s52, s14
	s_addc_u32 s53, s53, s15
	s_add_i32 s65, s62, s31
	global_load_lds_dwordx4 v[226:227], off
	v_lshl_add_u64 v[228:229], s[52:53], 0, v[130:131]
	s_mov_b32 m0, s65
	v_lshl_add_u64 v[230:231], s[52:53], 0, v[134:135]
	global_load_lds_dwordx4 v[228:229], off
	s_add_i32 m0, s65, 0x2000
	v_lshl_add_u64 v[232:233], s[46:47], 0, v[128:129]
	global_load_lds_dwordx4 v[230:231], off
	v_lshl_add_u64 v[234:235], s[46:47], 0, v[132:133]
	s_waitcnt vmcnt(6)
	s_waitcnt lgkmcnt(0)
	s_barrier
	s_setprio 1
	s_waitcnt lgkmcnt(0)
	v_mfma_f32_16x16x32_bf16 v[60:63], v[144:147], v[186:189], 0
	v_mfma_f32_16x16x32_bf16 v[56:59], v[160:163], v[186:189], 0
	v_mfma_f32_16x16x32_bf16 v[44:47], v[144:147], v[194:197], 0
	v_mfma_f32_16x16x32_bf16 v[40:43], v[160:163], v[194:197], 0
	v_mfma_f32_16x16x32_bf16 v[28:31], v[144:147], v[202:205], 0
	v_mfma_f32_16x16x32_bf16 v[24:27], v[160:163], v[202:205], 0
	v_mfma_f32_16x16x32_bf16 v[12:15], v[144:147], v[210:213], 0
	v_mfma_f32_16x16x32_bf16 v[8:11], v[160:163], v[210:213], 0
	v_mfma_f32_16x16x32_bf16 v[60:63], v[156:159], v[190:193], v[60:63]
	v_mfma_f32_16x16x32_bf16 v[56:59], v[164:167], v[190:193], v[56:59]
	v_mfma_f32_16x16x32_bf16 v[44:47], v[156:159], v[198:201], v[44:47]
	v_mfma_f32_16x16x32_bf16 v[40:43], v[164:167], v[198:201], v[40:43]
	v_mfma_f32_16x16x32_bf16 v[28:31], v[156:159], v[206:209], v[28:31]
	v_mfma_f32_16x16x32_bf16 v[24:27], v[164:167], v[206:209], v[24:27]
	v_mfma_f32_16x16x32_bf16 v[12:15], v[156:159], v[214:217], v[12:15]
	v_mfma_f32_16x16x32_bf16 v[8:11], v[164:167], v[214:217], v[8:11]
	s_setprio 0
	s_setprio 1
	v_mfma_f32_16x16x32_bf16 v[52:55], v[168:171], v[186:189], 0
	v_mfma_f32_16x16x32_bf16 v[48:51], v[176:179], v[186:189], 0
	v_mfma_f32_16x16x32_bf16 v[36:39], v[168:171], v[194:197], 0
	v_mfma_f32_16x16x32_bf16 v[32:35], v[176:179], v[194:197], 0
	v_mfma_f32_16x16x32_bf16 v[20:23], v[168:171], v[202:205], 0
	v_mfma_f32_16x16x32_bf16 v[16:19], v[176:179], v[202:205], 0
	v_mfma_f32_16x16x32_bf16 v[4:7], v[168:171], v[210:213], 0
	v_mfma_f32_16x16x32_bf16 v[0:3], v[176:179], v[210:213], 0
	v_mfma_f32_16x16x32_bf16 v[52:55], v[172:175], v[190:193], v[52:55]
	v_mfma_f32_16x16x32_bf16 v[48:51], v[180:183], v[190:193], v[48:51]
	v_mfma_f32_16x16x32_bf16 v[36:39], v[172:175], v[198:201], v[36:39]
	v_mfma_f32_16x16x32_bf16 v[32:35], v[180:183], v[198:201], v[32:35]
	v_mfma_f32_16x16x32_bf16 v[20:23], v[172:175], v[206:209], v[20:23]
	v_mfma_f32_16x16x32_bf16 v[16:19], v[180:183], v[206:209], v[16:19]
	v_mfma_f32_16x16x32_bf16 v[4:7], v[172:175], v[214:217], v[4:7]
	v_mfma_f32_16x16x32_bf16 v[0:3], v[180:183], v[214:217], v[0:3]
	s_setprio 0
	s_barrier
	s_add_i32 s52, 0, 0x18000
	v_add_u32_e32 v155, s52, v149
	s_add_i32 s53, 0, 0x1c000
	ds_read_b128 v[144:147], v155
	ds_read_b128 v[156:159], v155 offset:1024
	ds_read_b128 v[160:163], v155 offset:2048
	ds_read_b128 v[164:167], v155 offset:3072
	v_add_u32_e32 v155, s53, v149
	ds_read_b128 v[168:171], v155
	ds_read_b128 v[172:175], v155 offset:1024
	ds_read_b128 v[176:179], v155 offset:2048
	ds_read_b128 v[180:183], v155 offset:3072
	s_add_u32 s46, s46, s14
	s_addc_u32 s47, s47, s15
	s_mov_b32 m0, s50
	s_nop 0
	global_load_lds_dwordx4 v[232:233], off
	s_mov_b32 m0, s51
	s_nop 0
	global_load_lds_dwordx4 v[234:235], off
	s_mov_b32 m0, s54
	v_lshl_add_u64 v[236:237], s[46:47], 0, v[128:129]
	ds_read_b128 v[186:189], v153 offset:32768
	ds_read_b128 v[190:193], v153 offset:33792
	ds_read_b128 v[194:197], v153 offset:34816
	ds_read_b128 v[198:201], v153 offset:35840
	ds_read_b128 v[202:205], v153 offset:36864
	ds_read_b128 v[206:209], v153 offset:37888
	ds_read_b128 v[210:213], v153 offset:38912
	ds_read_b128 v[214:217], v153 offset:39936
	global_load_lds_dwordx4 v[236:237], off
	v_lshl_add_u64 v[236:237], s[46:47], 0, v[132:133]
	s_mov_b32 m0, s55
	s_nop 0
	global_load_lds_dwordx4 v[236:237], off
	s_waitcnt vmcnt(8)
	s_waitcnt lgkmcnt(0)
	s_barrier
	s_setprio 1
	s_waitcnt lgkmcnt(0)
	v_mfma_f32_16x16x32_bf16 v[124:127], v[144:147], v[186:189], v[124:127]
	v_mfma_f32_16x16x32_bf16 v[120:123], v[160:163], v[186:189], v[120:123]
	v_mfma_f32_16x16x32_bf16 v[108:111], v[144:147], v[194:197], v[108:111]
	v_mfma_f32_16x16x32_bf16 v[104:107], v[160:163], v[194:197], v[104:107]
	v_mfma_f32_16x16x32_bf16 v[92:95], v[144:147], v[202:205], v[92:95]
	v_mfma_f32_16x16x32_bf16 v[88:91], v[160:163], v[202:205], v[88:91]
	v_mfma_f32_16x16x32_bf16 v[76:79], v[144:147], v[210:213], v[76:79]
	v_mfma_f32_16x16x32_bf16 v[72:75], v[160:163], v[210:213], v[72:75]
	v_mfma_f32_16x16x32_bf16 v[124:127], v[156:159], v[190:193], v[124:127]
	v_mfma_f32_16x16x32_bf16 v[120:123], v[164:167], v[190:193], v[120:123]
	v_mfma_f32_16x16x32_bf16 v[108:111], v[156:159], v[198:201], v[108:111]
	v_mfma_f32_16x16x32_bf16 v[104:107], v[164:167], v[198:201], v[104:107]
	v_mfma_f32_16x16x32_bf16 v[92:95], v[156:159], v[206:209], v[92:95]
	v_mfma_f32_16x16x32_bf16 v[88:91], v[164:167], v[206:209], v[88:91]
	v_mfma_f32_16x16x32_bf16 v[76:79], v[156:159], v[214:217], v[76:79]
	v_mfma_f32_16x16x32_bf16 v[72:75], v[164:167], v[214:217], v[72:75]
	s_setprio 0
	s_setprio 1
	v_mfma_f32_16x16x32_bf16 v[116:119], v[168:171], v[186:189], v[116:119]
	v_mfma_f32_16x16x32_bf16 v[112:115], v[176:179], v[186:189], v[112:115]
	v_mfma_f32_16x16x32_bf16 v[100:103], v[168:171], v[194:197], v[100:103]
	v_mfma_f32_16x16x32_bf16 v[96:99], v[176:179], v[194:197], v[96:99]
	v_mfma_f32_16x16x32_bf16 v[84:87], v[168:171], v[202:205], v[84:87]
	v_mfma_f32_16x16x32_bf16 v[80:83], v[176:179], v[202:205], v[80:83]
	v_mfma_f32_16x16x32_bf16 v[68:71], v[168:171], v[210:213], v[68:71]
	v_mfma_f32_16x16x32_bf16 v[64:67], v[176:179], v[210:213], v[64:67]
	v_mfma_f32_16x16x32_bf16 v[116:119], v[172:175], v[190:193], v[116:119]
	v_mfma_f32_16x16x32_bf16 v[112:115], v[180:183], v[190:193], v[112:115]
	v_mfma_f32_16x16x32_bf16 v[100:103], v[172:175], v[198:201], v[100:103]
	v_mfma_f32_16x16x32_bf16 v[96:99], v[180:183], v[198:201], v[96:99]
	v_mfma_f32_16x16x32_bf16 v[84:87], v[172:175], v[206:209], v[84:87]
	v_mfma_f32_16x16x32_bf16 v[80:83], v[180:183], v[206:209], v[80:83]
	v_mfma_f32_16x16x32_bf16 v[68:71], v[172:175], v[214:217], v[68:71]
	v_mfma_f32_16x16x32_bf16 v[64:67], v[180:183], v[214:217], v[64:67]
	s_setprio 0
	s_barrier
	s_add_i32 s46, s52, s31
	v_lshl_add_u64 v[224:225], v[224:225], 0, s[36:37]
	s_mov_b32 m0, s46
	ds_read_b128 v[186:189], v153 offset:49152
	ds_read_b128 v[190:193], v153 offset:50176
	ds_read_b128 v[194:197], v153 offset:51200
	ds_read_b128 v[198:201], v153 offset:52224
	ds_read_b128 v[202:205], v153 offset:53248
	ds_read_b128 v[206:209], v153 offset:54272
	ds_read_b128 v[210:213], v153 offset:55296
	ds_read_b128 v[214:217], v153 offset:56320
	global_load_lds_dwordx4 v[224:225], off
	v_lshl_add_u64 v[224:225], v[226:227], 0, s[36:37]
	s_add_i32 m0, s46, 0x2000
	s_add_i32 s46, s53, s31
	global_load_lds_dwordx4 v[224:225], off
	v_lshl_add_u64 v[224:225], v[228:229], 0, s[36:37]
	s_mov_b32 m0, s46
	s_nop 0
	global_load_lds_dwordx4 v[224:225], off
	v_lshl_add_u64 v[224:225], v[230:231], 0, s[36:37]
	s_add_i32 m0, s46, 0x2000
	s_nop 0
	global_load_lds_dwordx4 v[224:225], off
	s_waitcnt vmcnt(6)
	s_waitcnt lgkmcnt(0)
	s_barrier
	s_setprio 1
	s_waitcnt lgkmcnt(0)
	v_mfma_f32_16x16x32_bf16 v[60:63], v[144:147], v[186:189], v[60:63]
	v_mfma_f32_16x16x32_bf16 v[56:59], v[160:163], v[186:189], v[56:59]
	v_mfma_f32_16x16x32_bf16 v[44:47], v[144:147], v[194:197], v[44:47]
	v_mfma_f32_16x16x32_bf16 v[40:43], v[160:163], v[194:197], v[40:43]
	v_mfma_f32_16x16x32_bf16 v[28:31], v[144:147], v[202:205], v[28:31]
	v_mfma_f32_16x16x32_bf16 v[24:27], v[160:163], v[202:205], v[24:27]
	v_mfma_f32_16x16x32_bf16 v[12:15], v[144:147], v[210:213], v[12:15]
	v_mfma_f32_16x16x32_bf16 v[8:11], v[160:163], v[210:213], v[8:11]
	v_mfma_f32_16x16x32_bf16 v[60:63], v[156:159], v[190:193], v[60:63]
	v_mfma_f32_16x16x32_bf16 v[56:59], v[164:167], v[190:193], v[56:59]
	v_mfma_f32_16x16x32_bf16 v[44:47], v[156:159], v[198:201], v[44:47]
	v_mfma_f32_16x16x32_bf16 v[40:43], v[164:167], v[198:201], v[40:43]
	v_mfma_f32_16x16x32_bf16 v[28:31], v[156:159], v[206:209], v[28:31]
	v_mfma_f32_16x16x32_bf16 v[24:27], v[164:167], v[206:209], v[24:27]
	v_mfma_f32_16x16x32_bf16 v[12:15], v[156:159], v[214:217], v[12:15]
	v_mfma_f32_16x16x32_bf16 v[8:11], v[164:167], v[214:217], v[8:11]
	s_setprio 0
	s_setprio 1
	v_mfma_f32_16x16x32_bf16 v[52:55], v[168:171], v[186:189], v[52:55]
	v_mfma_f32_16x16x32_bf16 v[48:51], v[176:179], v[186:189], v[48:51]
	v_mfma_f32_16x16x32_bf16 v[36:39], v[168:171], v[194:197], v[36:39]
	v_mfma_f32_16x16x32_bf16 v[32:35], v[176:179], v[194:197], v[32:35]
	v_mfma_f32_16x16x32_bf16 v[20:23], v[168:171], v[202:205], v[20:23]
	v_mfma_f32_16x16x32_bf16 v[16:19], v[176:179], v[202:205], v[16:19]
	v_mfma_f32_16x16x32_bf16 v[4:7], v[168:171], v[210:213], v[4:7]
	v_mfma_f32_16x16x32_bf16 v[0:3], v[176:179], v[210:213], v[0:3]
	v_mfma_f32_16x16x32_bf16 v[52:55], v[172:175], v[190:193], v[52:55]
	v_mfma_f32_16x16x32_bf16 v[48:51], v[180:183], v[190:193], v[48:51]
	v_mfma_f32_16x16x32_bf16 v[36:39], v[172:175], v[198:201], v[36:39]
	v_mfma_f32_16x16x32_bf16 v[32:35], v[180:183], v[198:201], v[32:35]
	v_mfma_f32_16x16x32_bf16 v[20:23], v[172:175], v[206:209], v[20:23]
	v_mfma_f32_16x16x32_bf16 v[16:19], v[180:183], v[206:209], v[16:19]
	v_mfma_f32_16x16x32_bf16 v[4:7], v[172:175], v[214:217], v[4:7]
	v_mfma_f32_16x16x32_bf16 v[0:3], v[180:183], v[214:217], v[0:3]
	s_setprio 0
	s_barrier
	s_add_u32 s4, s4, 0x100
	s_addc_u32 s5, s5, 0
	s_add_u32 s33, s33, 0x100
	s_addc_u32 s48, s48, 0
	s_cmp_ge_i32 s49, s59
	s_mov_b32 s46, s49
	s_cbranch_scc1 .LBB0_1113
.LBB0_1112:
	ds_read_b128 v[144:147], v151
	ds_read_b128 v[156:159], v151 offset:1024
	ds_read_b128 v[160:163], v151 offset:2048
	ds_read_b128 v[164:167], v151 offset:3072
	ds_read_b128 v[168:171], v152
	ds_read_b128 v[172:175], v152 offset:1024
	ds_read_b128 v[176:179], v152 offset:2048
	ds_read_b128 v[180:183], v152 offset:3072
	s_add_i32 s49, s46, 2
	s_add_u32 s52, s4, 0x80
	s_addc_u32 s47, s5, 0
	s_cmp_eq_u32 s60, s46
	s_cselect_b32 s46, s42, s52
	s_cselect_b32 s47, s43, s47
	s_cselect_b32 s53, s45, s48
	s_cselect_b32 s52, s44, s33
	v_lshl_add_u64 v[224:225], v[232:233], 0, s[36:37]
	s_mov_b32 m0, s57
	s_nop 0
	global_load_lds_dwordx4 v[224:225], off
	v_lshl_add_u64 v[224:225], v[234:235], 0, s[36:37]
	s_mov_b32 m0, s58
	s_nop 0
	global_load_lds_dwordx4 v[224:225], off
	v_lshl_add_u64 v[224:225], s[4:5], 0, v[136:137]
	s_add_i32 m0, s50, 0xc000
	ds_read_b128 v[186:189], v153
	ds_read_b128 v[190:193], v153 offset:1024
	ds_read_b128 v[194:197], v153 offset:2048
	ds_read_b128 v[198:201], v153 offset:3072
	ds_read_b128 v[202:205], v153 offset:4096
	ds_read_b128 v[206:209], v153 offset:5120
	ds_read_b128 v[210:213], v153 offset:6144
	ds_read_b128 v[214:217], v153 offset:7168
	global_load_lds_dwordx4 v[224:225], off
	v_lshl_add_u64 v[224:225], s[4:5], 0, v[138:139]
	s_add_i32 m0, s50, 0xe000
	s_nop 0
	global_load_lds_dwordx4 v[224:225], off
	s_waitcnt vmcnt(8)
	s_waitcnt lgkmcnt(0)
	s_barrier
	s_setprio 1
	s_waitcnt lgkmcnt(0)
	v_mfma_f32_16x16x32_bf16 v[124:127], v[144:147], v[186:189], v[124:127]
	v_mfma_f32_16x16x32_bf16 v[120:123], v[160:163], v[186:189], v[120:123]
	v_mfma_f32_16x16x32_bf16 v[108:111], v[144:147], v[194:197], v[108:111]
	v_mfma_f32_16x16x32_bf16 v[104:107], v[160:163], v[194:197], v[104:107]
	v_mfma_f32_16x16x32_bf16 v[92:95], v[144:147], v[202:205], v[92:95]
	v_mfma_f32_16x16x32_bf16 v[88:91], v[160:163], v[202:205], v[88:91]
	v_mfma_f32_16x16x32_bf16 v[76:79], v[144:147], v[210:213], v[76:79]
	v_mfma_f32_16x16x32_bf16 v[72:75], v[160:163], v[210:213], v[72:75]
	v_mfma_f32_16x16x32_bf16 v[124:127], v[156:159], v[190:193], v[124:127]
	v_mfma_f32_16x16x32_bf16 v[120:123], v[164:167], v[190:193], v[120:123]
	v_mfma_f32_16x16x32_bf16 v[108:111], v[156:159], v[198:201], v[108:111]
	v_mfma_f32_16x16x32_bf16 v[104:107], v[164:167], v[198:201], v[104:107]
	v_mfma_f32_16x16x32_bf16 v[92:95], v[156:159], v[206:209], v[92:95]
	v_mfma_f32_16x16x32_bf16 v[88:91], v[164:167], v[206:209], v[88:91]
	v_mfma_f32_16x16x32_bf16 v[76:79], v[156:159], v[214:217], v[76:79]
	v_mfma_f32_16x16x32_bf16 v[72:75], v[164:167], v[214:217], v[72:75]
	s_setprio 0
	s_setprio 1
	v_mfma_f32_16x16x32_bf16 v[116:119], v[168:171], v[186:189], v[116:119]
	v_mfma_f32_16x16x32_bf16 v[112:115], v[176:179], v[186:189], v[112:115]
	v_mfma_f32_16x16x32_bf16 v[100:103], v[168:171], v[194:197], v[100:103]
	v_mfma_f32_16x16x32_bf16 v[96:99], v[176:179], v[194:197], v[96:99]
	v_mfma_f32_16x16x32_bf16 v[84:87], v[168:171], v[202:205], v[84:87]
	v_mfma_f32_16x16x32_bf16 v[80:83], v[176:179], v[202:205], v[80:83]
	v_mfma_f32_16x16x32_bf16 v[68:71], v[168:171], v[210:213], v[68:71]
	v_mfma_f32_16x16x32_bf16 v[64:67], v[176:179], v[210:213], v[64:67]
	v_mfma_f32_16x16x32_bf16 v[116:119], v[172:175], v[190:193], v[116:119]
	v_mfma_f32_16x16x32_bf16 v[112:115], v[180:183], v[190:193], v[112:115]
	v_mfma_f32_16x16x32_bf16 v[100:103], v[172:175], v[198:201], v[100:103]
	v_mfma_f32_16x16x32_bf16 v[96:99], v[180:183], v[198:201], v[96:99]
	v_mfma_f32_16x16x32_bf16 v[84:87], v[172:175], v[206:209], v[84:87]
	v_mfma_f32_16x16x32_bf16 v[80:83], v[180:183], v[206:209], v[80:83]
	v_mfma_f32_16x16x32_bf16 v[68:71], v[172:175], v[214:217], v[68:71]
	v_mfma_f32_16x16x32_bf16 v[64:67], v[180:183], v[214:217], v[64:67]
	s_setprio 0
	s_barrier
	s_add_i32 s65, s61, s31
	v_lshl_add_u64 v[224:225], s[52:53], 0, v[130:131]
	s_mov_b32 m0, s65
	ds_read_b128 v[186:189], v153 offset:16384
	ds_read_b128 v[190:193], v153 offset:17408
	ds_read_b128 v[194:197], v153 offset:18432
	ds_read_b128 v[198:201], v153 offset:19456
	ds_read_b128 v[202:205], v153 offset:20480
	ds_read_b128 v[206:209], v153 offset:21504
	ds_read_b128 v[210:213], v153 offset:22528
	ds_read_b128 v[214:217], v153 offset:23552
	global_load_lds_dwordx4 v[224:225], off
	s_add_i32 m0, s65, 0x2000
	v_lshl_add_u64 v[226:227], s[52:53], 0, v[134:135]
	s_add_u32 s52, s52, s14
	s_addc_u32 s53, s53, s15
	s_add_i32 s65, s62, s31
	global_load_lds_dwordx4 v[226:227], off
	v_lshl_add_u64 v[228:229], s[52:53], 0, v[130:131]
	s_mov_b32 m0, s65
	v_lshl_add_u64 v[230:231], s[52:53], 0, v[134:135]
	global_load_lds_dwordx4 v[228:229], off
	s_add_i32 m0, s65, 0x2000
	v_lshl_add_u64 v[232:233], s[46:47], 0, v[128:129]
	global_load_lds_dwordx4 v[230:231], off
	v_lshl_add_u64 v[234:235], s[46:47], 0, v[132:133]
	s_waitcnt vmcnt(6)
	s_waitcnt lgkmcnt(0)
	s_barrier
	s_setprio 1
	s_waitcnt lgkmcnt(0)
	v_mfma_f32_16x16x32_bf16 v[60:63], v[144:147], v[186:189], v[60:63]
	v_mfma_f32_16x16x32_bf16 v[56:59], v[160:163], v[186:189], v[56:59]
	v_mfma_f32_16x16x32_bf16 v[44:47], v[144:147], v[194:197], v[44:47]
	v_mfma_f32_16x16x32_bf16 v[40:43], v[160:163], v[194:197], v[40:43]
	v_mfma_f32_16x16x32_bf16 v[28:31], v[144:147], v[202:205], v[28:31]
	v_mfma_f32_16x16x32_bf16 v[24:27], v[160:163], v[202:205], v[24:27]
	v_mfma_f32_16x16x32_bf16 v[12:15], v[144:147], v[210:213], v[12:15]
	v_mfma_f32_16x16x32_bf16 v[8:11], v[160:163], v[210:213], v[8:11]
	v_mfma_f32_16x16x32_bf16 v[60:63], v[156:159], v[190:193], v[60:63]
	v_mfma_f32_16x16x32_bf16 v[56:59], v[164:167], v[190:193], v[56:59]
	v_mfma_f32_16x16x32_bf16 v[44:47], v[156:159], v[198:201], v[44:47]
	v_mfma_f32_16x16x32_bf16 v[40:43], v[164:167], v[198:201], v[40:43]
	v_mfma_f32_16x16x32_bf16 v[28:31], v[156:159], v[206:209], v[28:31]
	v_mfma_f32_16x16x32_bf16 v[24:27], v[164:167], v[206:209], v[24:27]
	v_mfma_f32_16x16x32_bf16 v[12:15], v[156:159], v[214:217], v[12:15]
	v_mfma_f32_16x16x32_bf16 v[8:11], v[164:167], v[214:217], v[8:11]
	s_setprio 0
	s_setprio 1
	v_mfma_f32_16x16x32_bf16 v[52:55], v[168:171], v[186:189], v[52:55]
	v_mfma_f32_16x16x32_bf16 v[48:51], v[176:179], v[186:189], v[48:51]
	v_mfma_f32_16x16x32_bf16 v[36:39], v[168:171], v[194:197], v[36:39]
	v_mfma_f32_16x16x32_bf16 v[32:35], v[176:179], v[194:197], v[32:35]
	v_mfma_f32_16x16x32_bf16 v[20:23], v[168:171], v[202:205], v[20:23]
	v_mfma_f32_16x16x32_bf16 v[16:19], v[176:179], v[202:205], v[16:19]
	v_mfma_f32_16x16x32_bf16 v[4:7], v[168:171], v[210:213], v[4:7]
	v_mfma_f32_16x16x32_bf16 v[0:3], v[176:179], v[210:213], v[0:3]
	v_mfma_f32_16x16x32_bf16 v[52:55], v[172:175], v[190:193], v[52:55]
	v_mfma_f32_16x16x32_bf16 v[48:51], v[180:183], v[190:193], v[48:51]
	v_mfma_f32_16x16x32_bf16 v[36:39], v[172:175], v[198:201], v[36:39]
	v_mfma_f32_16x16x32_bf16 v[32:35], v[180:183], v[198:201], v[32:35]
	v_mfma_f32_16x16x32_bf16 v[20:23], v[172:175], v[206:209], v[20:23]
	v_mfma_f32_16x16x32_bf16 v[16:19], v[180:183], v[206:209], v[16:19]
	v_mfma_f32_16x16x32_bf16 v[4:7], v[172:175], v[214:217], v[4:7]
	v_mfma_f32_16x16x32_bf16 v[0:3], v[180:183], v[214:217], v[0:3]
	s_setprio 0
	s_barrier
	s_add_i32 s52, 0, 0x18000
	v_add_u32_e32 v155, s52, v149
	s_add_i32 s53, 0, 0x1c000
	ds_read_b128 v[144:147], v155
	ds_read_b128 v[156:159], v155 offset:1024
	ds_read_b128 v[160:163], v155 offset:2048
	ds_read_b128 v[164:167], v155 offset:3072
	v_add_u32_e32 v155, s53, v149
	ds_read_b128 v[168:171], v155
	ds_read_b128 v[172:175], v155 offset:1024
	ds_read_b128 v[176:179], v155 offset:2048
	ds_read_b128 v[180:183], v155 offset:3072
	s_add_u32 s46, s46, s14
	s_addc_u32 s47, s47, s15
	s_mov_b32 m0, s50
	s_nop 0
	global_load_lds_dwordx4 v[232:233], off
	s_mov_b32 m0, s51
	s_nop 0
	global_load_lds_dwordx4 v[234:235], off
	s_mov_b32 m0, s54
	v_lshl_add_u64 v[236:237], s[46:47], 0, v[128:129]
	ds_read_b128 v[186:189], v153 offset:32768
	ds_read_b128 v[190:193], v153 offset:33792
	ds_read_b128 v[194:197], v153 offset:34816
	ds_read_b128 v[198:201], v153 offset:35840
	ds_read_b128 v[202:205], v153 offset:36864
	ds_read_b128 v[206:209], v153 offset:37888
	ds_read_b128 v[210:213], v153 offset:38912
	ds_read_b128 v[214:217], v153 offset:39936
	global_load_lds_dwordx4 v[236:237], off
	v_lshl_add_u64 v[236:237], s[46:47], 0, v[132:133]
	s_mov_b32 m0, s55
	s_nop 0
	global_load_lds_dwordx4 v[236:237], off
	s_waitcnt vmcnt(8)
	s_waitcnt lgkmcnt(0)
	s_barrier
	s_setprio 1
	s_waitcnt lgkmcnt(0)
	v_mfma_f32_16x16x32_bf16 v[124:127], v[144:147], v[186:189], v[124:127]
	v_mfma_f32_16x16x32_bf16 v[120:123], v[160:163], v[186:189], v[120:123]
	v_mfma_f32_16x16x32_bf16 v[108:111], v[144:147], v[194:197], v[108:111]
	v_mfma_f32_16x16x32_bf16 v[104:107], v[160:163], v[194:197], v[104:107]
	v_mfma_f32_16x16x32_bf16 v[92:95], v[144:147], v[202:205], v[92:95]
	v_mfma_f32_16x16x32_bf16 v[88:91], v[160:163], v[202:205], v[88:91]
	v_mfma_f32_16x16x32_bf16 v[76:79], v[144:147], v[210:213], v[76:79]
	v_mfma_f32_16x16x32_bf16 v[72:75], v[160:163], v[210:213], v[72:75]
	v_mfma_f32_16x16x32_bf16 v[124:127], v[156:159], v[190:193], v[124:127]
	v_mfma_f32_16x16x32_bf16 v[120:123], v[164:167], v[190:193], v[120:123]
	v_mfma_f32_16x16x32_bf16 v[108:111], v[156:159], v[198:201], v[108:111]
	v_mfma_f32_16x16x32_bf16 v[104:107], v[164:167], v[198:201], v[104:107]
	v_mfma_f32_16x16x32_bf16 v[92:95], v[156:159], v[206:209], v[92:95]
	v_mfma_f32_16x16x32_bf16 v[88:91], v[164:167], v[206:209], v[88:91]
	v_mfma_f32_16x16x32_bf16 v[76:79], v[156:159], v[214:217], v[76:79]
	v_mfma_f32_16x16x32_bf16 v[72:75], v[164:167], v[214:217], v[72:75]
	s_setprio 0
	s_setprio 1
	v_mfma_f32_16x16x32_bf16 v[116:119], v[168:171], v[186:189], v[116:119]
	v_mfma_f32_16x16x32_bf16 v[112:115], v[176:179], v[186:189], v[112:115]
	v_mfma_f32_16x16x32_bf16 v[100:103], v[168:171], v[194:197], v[100:103]
	v_mfma_f32_16x16x32_bf16 v[96:99], v[176:179], v[194:197], v[96:99]
	v_mfma_f32_16x16x32_bf16 v[84:87], v[168:171], v[202:205], v[84:87]
	v_mfma_f32_16x16x32_bf16 v[80:83], v[176:179], v[202:205], v[80:83]
	v_mfma_f32_16x16x32_bf16 v[68:71], v[168:171], v[210:213], v[68:71]
	v_mfma_f32_16x16x32_bf16 v[64:67], v[176:179], v[210:213], v[64:67]
	v_mfma_f32_16x16x32_bf16 v[116:119], v[172:175], v[190:193], v[116:119]
	v_mfma_f32_16x16x32_bf16 v[112:115], v[180:183], v[190:193], v[112:115]
	v_mfma_f32_16x16x32_bf16 v[100:103], v[172:175], v[198:201], v[100:103]
	v_mfma_f32_16x16x32_bf16 v[96:99], v[180:183], v[198:201], v[96:99]
	v_mfma_f32_16x16x32_bf16 v[84:87], v[172:175], v[206:209], v[84:87]
	v_mfma_f32_16x16x32_bf16 v[80:83], v[180:183], v[206:209], v[80:83]
	v_mfma_f32_16x16x32_bf16 v[68:71], v[172:175], v[214:217], v[68:71]
	v_mfma_f32_16x16x32_bf16 v[64:67], v[180:183], v[214:217], v[64:67]
	s_setprio 0
	s_barrier
	s_add_i32 s46, s52, s31
	v_lshl_add_u64 v[224:225], v[224:225], 0, s[36:37]
	s_mov_b32 m0, s46
	ds_read_b128 v[186:189], v153 offset:49152
	ds_read_b128 v[190:193], v153 offset:50176
	ds_read_b128 v[194:197], v153 offset:51200
	ds_read_b128 v[198:201], v153 offset:52224
	ds_read_b128 v[202:205], v153 offset:53248
	ds_read_b128 v[206:209], v153 offset:54272
	ds_read_b128 v[210:213], v153 offset:55296
	ds_read_b128 v[214:217], v153 offset:56320
	global_load_lds_dwordx4 v[224:225], off
	v_lshl_add_u64 v[224:225], v[226:227], 0, s[36:37]
	s_add_i32 m0, s46, 0x2000
	s_add_i32 s46, s53, s31
	global_load_lds_dwordx4 v[224:225], off
	v_lshl_add_u64 v[224:225], v[228:229], 0, s[36:37]
	s_mov_b32 m0, s46
	s_nop 0
	global_load_lds_dwordx4 v[224:225], off
	v_lshl_add_u64 v[224:225], v[230:231], 0, s[36:37]
	s_add_i32 m0, s46, 0x2000
	s_nop 0
	global_load_lds_dwordx4 v[224:225], off
	s_waitcnt vmcnt(6)
	s_waitcnt lgkmcnt(0)
	s_barrier
	s_setprio 1
	s_waitcnt lgkmcnt(0)
	v_mfma_f32_16x16x32_bf16 v[60:63], v[144:147], v[186:189], v[60:63]
	v_mfma_f32_16x16x32_bf16 v[56:59], v[160:163], v[186:189], v[56:59]
	v_mfma_f32_16x16x32_bf16 v[44:47], v[144:147], v[194:197], v[44:47]
	v_mfma_f32_16x16x32_bf16 v[40:43], v[160:163], v[194:197], v[40:43]
	v_mfma_f32_16x16x32_bf16 v[28:31], v[144:147], v[202:205], v[28:31]
	v_mfma_f32_16x16x32_bf16 v[24:27], v[160:163], v[202:205], v[24:27]
	v_mfma_f32_16x16x32_bf16 v[12:15], v[144:147], v[210:213], v[12:15]
	v_mfma_f32_16x16x32_bf16 v[8:11], v[160:163], v[210:213], v[8:11]
	v_mfma_f32_16x16x32_bf16 v[60:63], v[156:159], v[190:193], v[60:63]
	v_mfma_f32_16x16x32_bf16 v[56:59], v[164:167], v[190:193], v[56:59]
	v_mfma_f32_16x16x32_bf16 v[44:47], v[156:159], v[198:201], v[44:47]
	v_mfma_f32_16x16x32_bf16 v[40:43], v[164:167], v[198:201], v[40:43]
	v_mfma_f32_16x16x32_bf16 v[28:31], v[156:159], v[206:209], v[28:31]
	v_mfma_f32_16x16x32_bf16 v[24:27], v[164:167], v[206:209], v[24:27]
	v_mfma_f32_16x16x32_bf16 v[12:15], v[156:159], v[214:217], v[12:15]
	v_mfma_f32_16x16x32_bf16 v[8:11], v[164:167], v[214:217], v[8:11]
	s_setprio 0
	s_setprio 1
	v_mfma_f32_16x16x32_bf16 v[52:55], v[168:171], v[186:189], v[52:55]
	v_mfma_f32_16x16x32_bf16 v[48:51], v[176:179], v[186:189], v[48:51]
	v_mfma_f32_16x16x32_bf16 v[36:39], v[168:171], v[194:197], v[36:39]
	v_mfma_f32_16x16x32_bf16 v[32:35], v[176:179], v[194:197], v[32:35]
	v_mfma_f32_16x16x32_bf16 v[20:23], v[168:171], v[202:205], v[20:23]
	v_mfma_f32_16x16x32_bf16 v[16:19], v[176:179], v[202:205], v[16:19]
	v_mfma_f32_16x16x32_bf16 v[4:7], v[168:171], v[210:213], v[4:7]
	v_mfma_f32_16x16x32_bf16 v[0:3], v[176:179], v[210:213], v[0:3]
	v_mfma_f32_16x16x32_bf16 v[52:55], v[172:175], v[190:193], v[52:55]
	v_mfma_f32_16x16x32_bf16 v[48:51], v[180:183], v[190:193], v[48:51]
	v_mfma_f32_16x16x32_bf16 v[36:39], v[172:175], v[198:201], v[36:39]
	v_mfma_f32_16x16x32_bf16 v[32:35], v[180:183], v[198:201], v[32:35]
	v_mfma_f32_16x16x32_bf16 v[20:23], v[172:175], v[206:209], v[20:23]
	v_mfma_f32_16x16x32_bf16 v[16:19], v[180:183], v[206:209], v[16:19]
	v_mfma_f32_16x16x32_bf16 v[4:7], v[172:175], v[214:217], v[4:7]
	v_mfma_f32_16x16x32_bf16 v[0:3], v[180:183], v[214:217], v[0:3]
	s_setprio 0
	s_barrier
	s_add_u32 s4, s4, 0x100
	s_addc_u32 s5, s5, 0
	s_add_u32 s33, s33, 0x100
	s_addc_u32 s48, s48, 0
	s_cmp_ge_i32 s49, s59
	s_mov_b32 s46, s49
	s_cbranch_scc0 .LBB0_1112
	s_branch .LBB0_1113
